# QKV epilogue head-norm reductions via v_permlane16/32_swap instead of ds_bpermute round trips
# speedup vs baseline: 1.0144x; 1.0024x over previous
; DI u16 f2bf(float a) { return (u16)(pack_bf16(a, 0.f) & 0xffffu); }
;   DI void operator()(const f32x4 (&acc)[2][2][4][2], const Unit& u, int wr, int wc, int fr, int fq) const {
;     ...
;         const int t = u.pm * BM + ai * HALF + wr * 64 + m * 16 + fr;
;         int b, pos;
;         if (rowbase == 0) { b = t >> 12; pos = t & 4095; } else { b = t >> 8; pos = 4096 + (t & 255); }
;         u16* base = qkv + (size_t)(b * 32 + chunk) * LTOT * 64;
;         if (isV) {
; #pragma unroll
;           for (int bj = 0; bj < 2; ++bj)
; #pragma unroll
;             for (int n = 0; n < 2; ++n)
; #pragma unroll
;               for (int e = 0; e < 4; ++e) {
;                 int d = 32 * bj + 8 * fq + 4 * n + e;
;                 base[(size_t)d * LTOT + pos] = f2bf(acc[ai][bj][m][n][e]);
;               }
;         } else {
;           float ss = 0.f;
; #pragma unroll
;           for (int bj = 0; bj < 2; ++bj)
; #pragma unroll
;             for (int n = 0; n < 2; ++n)
; #pragma unroll
;               for (int e = 0; e < 4; ++e) ss += acc[ai][bj][m][n][e] * acc[ai][bj][m][n][e];
;           ss += __shfl_xor(ss, 16);
;           ss += __shfl_xor(ss, 32);
;           const float rinv = rsqrtf(ss * (1.f / 64.f) + EPSV);
;           float o1[8], o2[8];
; #pragma unroll
;           for (int n = 0; n < 2; ++n) {
;             f32x4 cs0 = (f32x4){1.f, 0.f, 1.f, 0.f}, cs1 = cs0;
;             if (ropeT) { cs0 = csr[m & 1][n][0]; cs1 = csr[m & 1][n][1]; }
; #pragma unroll
;             for (int e = 0; e < 4; ++e) {
;               float x1 = acc[ai][0][m][n][e] * (rinv * qs) * g4[0][n][e];
;               float x2 = acc[ai][1][m][n][e] * (rinv * qs) * g4[1][n][e];
;               float c = (e < 2) ? cs0[2 * e] : cs1[2 * (e - 2)], s = (e < 2) ? cs0[2 * e + 1] : cs1[2 * (e - 2) + 1];
;               o1[n * 4 + e] = x1 * c - x2 * s;
;               o2[n * 4 + e] = x2 * c + x1 * s;
;             }
;           }
;           u16* dst = base + (size_t)pos * 64 + 8 * fq;
;           *(uint4*)(dst) = make_uint4(pack_bf16(o1[0], o1[1]), pack_bf16(o1[2], o1[3]), pack_bf16(o1[4], o1[5]), pack_bf16(o1[6], o1[7]));
;           *(uint4*)(dst + 32) = make_uint4(pack_bf16(o2[0], o2[1]), pack_bf16(o2[2], o2[3]), pack_bf16(o2[4], o2[5]), pack_bf16(o2[6], o2[7]));
.LBB0_536:
	s_xor_b64 s[52:53], s[8:9], -1
	s_or_b64 s[8:9], s[10:11], s[22:23]
	s_or_b64 vcc, s[24:25], s[8:9]
	s_ashr_i32 s8, s49, 7
	s_andn2_b32 s8, s8, 31
	s_add_i32 s8, s8, s48
	s_mul_hi_i32 s9, s8, 0x88000
	s_mul_i32 s8, s8, 0x88000
	s_add_u32 s10, s88, s8
	v_cndmask_b32_e64 v180, 0, 1, s[52:53]
	v_cndmask_b32_e32 v217, 1.0, v248, vcc
	s_addc_u32 s11, s89, s9
	s_mov_b64 s[22:23], -1
	v_cmp_ne_u32_e64 s[8:9], 1, v180
	s_andn2_b64 vcc, exec, s[52:53]
	v_lshlrev_b32_e32 v206, 1, v184
	s_cbranch_vccnz .LBB0_538
	v_mul_f32_e32 v180, v175, v175
	v_fmac_f32_e32 v180, v174, v174
	v_fmac_f32_e32 v180, v176, v176
	v_fmac_f32_e32 v180, v177, v177
	v_fmac_f32_e32 v180, v170, v170
	v_fmac_f32_e32 v180, v171, v171
	v_fmac_f32_e32 v180, v172, v172
	v_fmac_f32_e32 v180, v173, v173
	v_pk_mul_f32 v[220:221], v[166:167], v[166:167]
	v_pk_mul_f32 v[218:219], v[168:169], v[168:169]
	v_add_f32_e32 v180, v220, v180
	v_add_f32_e32 v180, v221, v180
	v_add_f32_e32 v180, v218, v180
	v_add_f32_e32 v180, v219, v180
	v_pk_mul_f32 v[220:221], v[162:163], v[162:163]
	v_add_f32_e32 v180, v220, v180
	v_pk_mul_f32 v[218:219], v[164:165], v[164:165]
	v_add_f32_e32 v180, v221, v180
	v_add_f32_e32 v180, v218, v180
	v_add_f32_e32 v180, v219, v180
	v_mov_b32_e32 v181, v180
	s_nop 1
	v_permlane16_swap_b32_e32 v180, v181
	s_mov_b32 s22, 0x800000
	v_mov_b32_e32 v226, v174
	v_mov_b32_e32 v227, v167
	s_waitcnt vmcnt(0)
	v_mov_b32_e32 v228, v74
	s_waitcnt lgkmcnt(0)
	v_add_f32_e32 v180, v180, v181
	v_mov_b32_e32 v229, v79
	v_mov_b32_e32 v230, v78
	v_mov_b32_e32 v181, v180
	s_nop 1
	v_permlane32_swap_b32_e32 v180, v181
	v_mov_b32_e32 v231, v75
	v_cndmask_b32_e64 v219, 0, v129, s[6:7]
	v_cndmask_b32_e64 v218, 1.0, v126, s[6:7]
	v_cndmask_b32_e64 v221, 1.0, v128, s[6:7]
	s_waitcnt lgkmcnt(0)
	v_add_f32_e32 v180, v180, v181
	v_fmamk_f32 v180, v180, 0x3c800000, v210
	v_mul_f32_e32 v181, 0x4b800000, v180
	v_cmp_gt_f32_e32 vcc, s22, v180
	v_cndmask_b32_e64 v220, 0, v127, s[6:7]
	v_mov_b32_e32 v233, v221
	v_cndmask_b32_e32 v180, v180, v181, vcc
	v_rsq_f32_e32 v180, v180
	v_mov_b32_e32 v232, v218
	v_cndmask_b32_e64 v223, 0, v125, s[6:7]
	v_cndmask_b32_e64 v222, 1.0, v122, s[6:7]
	v_mul_f32_e32 v181, 0x45800000, v180
	v_cndmask_b32_e32 v180, v180, v181, vcc
	v_mul_f32_e32 v208, v217, v180
	v_pk_mul_f32 v[226:227], v[226:227], v[208:209] op_sel_hi:[1,0]
	v_cndmask_b32_e64 v225, 1.0, v124, s[6:7]
	v_pk_mul_f32 v[226:227], v[228:229], v[226:227]
	v_mov_b32_e32 v228, v166
	v_mov_b32_e32 v229, v175
	v_pk_mul_f32 v[228:229], v[228:229], v[208:209] op_sel_hi:[1,0]
	v_mov_b32_e32 v234, v226
	v_pk_mul_f32 v[228:229], v[230:231], v[228:229]
	v_cndmask_b32_e64 v224, 0, v123, s[6:7]
	v_pk_mul_f32 v[230:231], v[218:219], v[228:229]
	v_mov_b32_e32 v235, v229
	v_pk_fma_f32 v[230:231], v[220:221], v[226:227], v[230:231]
	v_mov_b32_e32 v221, v219
	v_mov_b32_e32 v229, v227
	v_pk_mul_f32 v[218:219], v[220:221], v[228:229]
	v_mov_b32_e32 v220, v176
	v_mov_b32_e32 v221, v169
	v_pk_mul_f32 v[220:221], v[220:221], v[208:209] op_sel_hi:[1,0]
	v_mov_b32_e32 v226, v76
	v_mov_b32_e32 v227, v81
	v_pk_mul_f32 v[220:221], v[226:227], v[220:221]
	v_mov_b32_e32 v226, v168
	v_mov_b32_e32 v227, v177
	v_pk_mul_f32 v[226:227], v[226:227], v[208:209] op_sel_hi:[1,0]
	v_mov_b32_e32 v228, v80
	v_mov_b32_e32 v229, v77
	v_pk_mul_f32 v[226:227], v[228:229], v[226:227]
	v_pk_fma_f32 v[218:219], v[232:233], v[234:235], v[218:219] neg_lo:[0,0,1] neg_hi:[0,0,1]
	v_pk_mul_f32 v[228:229], v[222:223], v[226:227]
	v_mov_b32_e32 v233, v225
	v_pk_fma_f32 v[228:229], v[224:225], v[220:221], v[228:229]
	v_mov_b32_e32 v235, v227
	v_mov_b32_e32 v225, v223
	v_mov_b32_e32 v227, v221
	v_mov_b32_e32 v232, v222
	v_mov_b32_e32 v234, v220
	v_pk_mul_f32 v[220:221], v[224:225], v[226:227]
	v_mov_b32_e32 v236, v66
	v_pk_fma_f32 v[220:221], v[232:233], v[234:235], v[220:221] neg_lo:[0,0,1] neg_hi:[0,0,1]
	v_mov_b32_e32 v234, v170
	v_mov_b32_e32 v235, v163
	v_pk_mul_f32 v[234:235], v[234:235], v[208:209] op_sel_hi:[1,0]
	v_mov_b32_e32 v237, v71
	v_pk_mul_f32 v[234:235], v[236:237], v[234:235]
	v_mov_b32_e32 v236, v162
	v_mov_b32_e32 v237, v171
	v_pk_mul_f32 v[236:237], v[236:237], v[208:209] op_sel_hi:[1,0]
	v_mov_b32_e32 v238, v70
	v_mov_b32_e32 v239, v67
	v_cndmask_b32_e64 v223, 0, v121, s[6:7]
	v_cndmask_b32_e64 v222, 1.0, v118, s[6:7]
	v_pk_mul_f32 v[236:237], v[238:239], v[236:237]
	v_cndmask_b32_e64 v225, 1.0, v120, s[6:7]
	v_cndmask_b32_e64 v224, 0, v119, s[6:7]
	v_pk_mul_f32 v[238:239], v[222:223], v[236:237]
	v_mov_b32_e32 v241, v225
	v_pk_fma_f32 v[238:239], v[224:225], v[234:235], v[238:239]
	v_mov_b32_e32 v243, v237
	v_mov_b32_e32 v225, v223
	v_mov_b32_e32 v237, v235
	v_mov_b32_e32 v240, v222
	v_pk_mul_f32 v[222:223], v[224:225], v[236:237]
	v_mov_b32_e32 v224, v172
	v_mov_b32_e32 v225, v165
	v_mov_b32_e32 v242, v234
	v_pk_mul_f32 v[224:225], v[224:225], v[208:209] op_sel_hi:[1,0]
	v_mov_b32_e32 v234, v68
	v_mov_b32_e32 v235, v73
	v_pk_mul_f32 v[224:225], v[234:235], v[224:225]
	v_mov_b32_e32 v234, v164
	v_mov_b32_e32 v235, v173
	v_pk_mul_f32 v[234:235], v[234:235], v[208:209] op_sel_hi:[1,0]
	v_mov_b32_e32 v236, v72
	v_mov_b32_e32 v237, v69
	v_cndmask_b32_e64 v227, 0, v117, s[6:7]
	v_cndmask_b32_e64 v226, 1.0, v114, s[6:7]
	v_pk_mul_f32 v[234:235], v[236:237], v[234:235]
	v_cndmask_b32_e64 v233, 1.0, v116, s[6:7]
	v_cndmask_b32_e64 v232, 0, v115, s[6:7]
	v_pk_mul_f32 v[236:237], v[226:227], v[234:235]
	v_pk_fma_f32 v[222:223], v[240:241], v[242:243], v[222:223] neg_lo:[0,0,1] neg_hi:[0,0,1]
	v_pk_fma_f32 v[236:237], v[232:233], v[224:225], v[236:237]
	v_mov_b32_e32 v241, v233
	v_mov_b32_e32 v243, v235
	v_mov_b32_e32 v233, v227
	v_mov_b32_e32 v235, v225
	v_mov_b32_e32 v240, v226
	v_mov_b32_e32 v242, v224
	v_pk_mul_f32 v[224:225], v[232:233], v[234:235]
	v_lshlrev_b32_e32 v226, 7, v209
	v_mov_b32_e32 v227, v1
	v_pk_fma_f32 v[224:225], v[240:241], v[242:243], v[224:225] neg_lo:[0,0,1] neg_hi:[0,0,1]
	v_lshl_add_u64 v[226:227], s[10:11], 0, v[226:227]
	v_mov_b32_e32 v207, v1
	v_lshl_add_u64 v[226:227], v[226:227], 0, v[206:207]
	v_cvt_pk_bf16_f32 v218, v218, v219
	v_cvt_pk_bf16_f32 v219, v220, v221
	v_cvt_pk_bf16_f32 v220, v222, v223
	v_cvt_pk_bf16_f32 v221, v224, v225
	global_store_dwordx4 v[226:227], v[218:221], off
	s_mov_b64 s[22:23], 0
	s_nop 0
	v_cvt_pk_bf16_f32 v218, v230, v231
	v_cvt_pk_bf16_f32 v219, v228, v229
	v_cvt_pk_bf16_f32 v220, v238, v239
	v_cvt_pk_bf16_f32 v221, v236, v237
	global_store_dwordx4 v[226:227], v[218:221], off offset:64

; DI u16 f2bf(float a) { return (u16)(pack_bf16(a, 0.f) & 0xffffu); }
;   DI void operator()(const f32x4 (&acc)[2][2][4][2], const Unit& u, int wr, int wc, int fr, int fq) const {
;     ...
;         const int t = u.pm * BM + ai * HALF + wr * 64 + m * 16 + fr;
;         int b, pos;
;         if (rowbase == 0) { b = t >> 12; pos = t & 4095; } else { b = t >> 8; pos = 4096 + (t & 255); }
;         u16* base = qkv + (size_t)(b * 32 + chunk) * LTOT * 64;
;         if (isV) {
; #pragma unroll
;           for (int bj = 0; bj < 2; ++bj)
; #pragma unroll
;             for (int n = 0; n < 2; ++n)
; #pragma unroll
;               for (int e = 0; e < 4; ++e) {
;                 int d = 32 * bj + 8 * fq + 4 * n + e;
;                 base[(size_t)d * LTOT + pos] = f2bf(acc[ai][bj][m][n][e]);
;               }
;         } else {
;           float ss = 0.f;
; #pragma unroll
;           for (int bj = 0; bj < 2; ++bj)
; #pragma unroll
;             for (int n = 0; n < 2; ++n)
; #pragma unroll
;               for (int e = 0; e < 4; ++e) ss += acc[ai][bj][m][n][e] * acc[ai][bj][m][n][e];
;           ss += __shfl_xor(ss, 16);
;           ss += __shfl_xor(ss, 32);
;           const float rinv = rsqrtf(ss * (1.f / 64.f) + EPSV);
;           float o1[8], o2[8];
; #pragma unroll
;           for (int n = 0; n < 2; ++n) {
;             f32x4 cs0 = (f32x4){1.f, 0.f, 1.f, 0.f}, cs1 = cs0;
;             if (ropeT) { cs0 = csr[m & 1][n][0]; cs1 = csr[m & 1][n][1]; }
; #pragma unroll
;             for (int e = 0; e < 4; ++e) {
;               float x1 = acc[ai][0][m][n][e] * (rinv * qs) * g4[0][n][e];
;               float x2 = acc[ai][1][m][n][e] * (rinv * qs) * g4[1][n][e];
;               float c = (e < 2) ? cs0[2 * e] : cs1[2 * (e - 2)], s = (e < 2) ? cs0[2 * e + 1] : cs1[2 * (e - 2) + 1];
;               o1[n * 4 + e] = x1 * c - x2 * s;
;               o2[n * 4 + e] = x2 * c + x1 * s;
;             }
;           }
;           u16* dst = base + (size_t)pos * 64 + 8 * fq;
;           *(uint4*)(dst) = make_uint4(pack_bf16(o1[0], o1[1]), pack_bf16(o1[2], o1[3]), pack_bf16(o1[4], o1[5]), pack_bf16(o1[6], o1[7]));
;           *(uint4*)(dst + 32) = make_uint4(pack_bf16(o2[0], o2[1]), pack_bf16(o2[2], o2[3]), pack_bf16(o2[4], o2[5]), pack_bf16(o2[6], o2[7]));
.LBB0_540:
	s_add_i32 s10, s50, s42
	s_and_b32 s11, s10, 0xfd0
	s_ashr_i32 s10, s10, 7
	s_andn2_b32 s10, s10, 31
	s_add_i32 s10, s10, s48
	v_or_b32_e32 v162, s11, v214
	s_mul_hi_i32 s11, s10, 0x88000
	s_mul_i32 s10, s10, 0x88000
	s_add_u32 s10, s88, s10
	s_addc_u32 s11, s89, s11
	s_and_b64 vcc, exec, s[8:9]
	s_mov_b64 s[22:23], -1
	v_readlane_b32 s52, v253, 59
	v_readlane_b32 s53, v253, 60
	s_cbranch_vccnz .LBB0_542
	v_mul_f32_e32 v163, v159, v159
	v_fmac_f32_e32 v163, v158, v158
	v_fmac_f32_e32 v163, v160, v160
	v_fmac_f32_e32 v163, v161, v161
	v_fmac_f32_e32 v163, v154, v154
	v_fmac_f32_e32 v163, v155, v155
	v_fmac_f32_e32 v163, v156, v156
	v_fmac_f32_e32 v163, v157, v157
	v_pk_mul_f32 v[166:167], v[150:151], v[150:151]
	v_pk_mul_f32 v[164:165], v[152:153], v[152:153]
	v_add_f32_e32 v163, v166, v163
	v_add_f32_e32 v163, v167, v163
	v_add_f32_e32 v163, v164, v163
	v_add_f32_e32 v163, v165, v163
	v_pk_mul_f32 v[166:167], v[146:147], v[146:147]
	v_pk_mul_f32 v[164:165], v[148:149], v[148:149]
	v_add_f32_e32 v163, v166, v163
	v_add_f32_e32 v163, v167, v163
	v_add_f32_e32 v163, v164, v163
	v_add_f32_e32 v163, v165, v163
	s_mov_b32 s22, 0x800000
	v_mov_b32_e32 v174, v158
	v_mov_b32_e32 v164, v163
	s_nop 1
	v_permlane16_swap_b32_e32 v163, v164
	v_mov_b32_e32 v175, v151
	v_mov_b32_e32 v176, v74
	v_mov_b32_e32 v177, v79
	v_mov_b32_e32 v218, v78
	s_waitcnt lgkmcnt(0)
	v_add_f32_e32 v163, v163, v164
	v_mov_b32_e32 v219, v75
	v_cndmask_b32_e64 v167, 0, v97, s[6:7]
	v_mov_b32_e32 v164, v163
	s_nop 1
	v_permlane32_swap_b32_e32 v163, v164
	v_cndmask_b32_e64 v166, 1.0, v94, s[6:7]
	v_cndmask_b32_e64 v169, 1.0, v96, s[6:7]
	v_cndmask_b32_e64 v168, 0, v95, s[6:7]
	v_mov_b32_e32 v221, v169
	s_waitcnt lgkmcnt(0)
	v_add_f32_e32 v163, v163, v164
	v_fmamk_f32 v163, v163, 0x3c800000, v210
	v_mul_f32_e32 v164, 0x4b800000, v163
	v_cmp_gt_f32_e32 vcc, s22, v163
	v_mov_b32_e32 v220, v166
	v_cndmask_b32_e64 v171, 0, v101, s[6:7]
	v_cndmask_b32_e32 v163, v163, v164, vcc
	v_rsq_f32_e32 v163, v163
	v_cndmask_b32_e64 v170, 1.0, v98, s[6:7]
	v_cndmask_b32_e64 v173, 1.0, v100, s[6:7]
	v_cndmask_b32_e64 v172, 0, v99, s[6:7]
	v_mul_f32_e32 v164, 0x45800000, v163
	v_cndmask_b32_e32 v163, v163, v164, vcc
	v_mul_f32_e32 v164, v217, v163
	v_pk_mul_f32 v[174:175], v[174:175], v[164:165] op_sel_hi:[1,0]
	v_mov_b32_e32 v224, v66
	v_pk_mul_f32 v[174:175], v[176:177], v[174:175]
	v_mov_b32_e32 v176, v150
	v_mov_b32_e32 v177, v159
	v_pk_mul_f32 v[176:177], v[176:177], v[164:165] op_sel_hi:[1,0]
	v_mov_b32_e32 v222, v174
	v_pk_mul_f32 v[176:177], v[218:219], v[176:177]
	v_mov_b32_e32 v225, v71
	v_pk_mul_f32 v[218:219], v[166:167], v[176:177]
	v_mov_b32_e32 v223, v177
	v_pk_fma_f32 v[218:219], v[168:169], v[174:175], v[218:219]
	v_mov_b32_e32 v169, v167
	v_mov_b32_e32 v177, v175
	v_pk_mul_f32 v[166:167], v[168:169], v[176:177]
	v_mov_b32_e32 v168, v160
	v_mov_b32_e32 v169, v153
	v_pk_mul_f32 v[168:169], v[168:169], v[164:165] op_sel_hi:[1,0]
	v_mov_b32_e32 v174, v76
	v_mov_b32_e32 v175, v81
	v_pk_mul_f32 v[168:169], v[174:175], v[168:169]
	v_mov_b32_e32 v174, v152
	v_mov_b32_e32 v175, v161
	v_pk_mul_f32 v[174:175], v[174:175], v[164:165] op_sel_hi:[1,0]
	v_mov_b32_e32 v176, v80
	v_mov_b32_e32 v177, v77
	v_pk_mul_f32 v[174:175], v[176:177], v[174:175]
	v_pk_fma_f32 v[166:167], v[220:221], v[222:223], v[166:167] neg_lo:[0,0,1] neg_hi:[0,0,1]
	v_pk_mul_f32 v[176:177], v[170:171], v[174:175]
	v_mov_b32_e32 v221, v173
	v_pk_fma_f32 v[176:177], v[172:173], v[168:169], v[176:177]
	v_mov_b32_e32 v223, v175
	v_mov_b32_e32 v173, v171
	v_mov_b32_e32 v175, v169
	v_mov_b32_e32 v220, v170
	v_mov_b32_e32 v222, v168
	v_pk_mul_f32 v[168:169], v[172:173], v[174:175]
	v_mov_b32_e32 v226, v70
	v_pk_fma_f32 v[168:169], v[220:221], v[222:223], v[168:169] neg_lo:[0,0,1] neg_hi:[0,0,1]
	v_mov_b32_e32 v222, v154
	v_mov_b32_e32 v223, v147
	v_pk_mul_f32 v[222:223], v[222:223], v[164:165] op_sel_hi:[1,0]
	v_mov_b32_e32 v227, v67
	v_pk_mul_f32 v[222:223], v[224:225], v[222:223]
	v_mov_b32_e32 v224, v146
	v_mov_b32_e32 v225, v155
	v_pk_mul_f32 v[224:225], v[224:225], v[164:165] op_sel_hi:[1,0]
	v_cndmask_b32_e64 v171, 0, v89, s[6:7]
	v_cndmask_b32_e64 v170, 1.0, v86, s[6:7]
	v_pk_mul_f32 v[224:225], v[226:227], v[224:225]
	v_cndmask_b32_e64 v173, 1.0, v88, s[6:7]
	v_cndmask_b32_e64 v172, 0, v87, s[6:7]
	v_pk_mul_f32 v[226:227], v[170:171], v[224:225]
	v_mov_b32_e32 v229, v173
	v_pk_fma_f32 v[226:227], v[172:173], v[222:223], v[226:227]
	v_mov_b32_e32 v231, v225
	v_mov_b32_e32 v173, v171
	v_mov_b32_e32 v225, v223
	v_mov_b32_e32 v228, v170
	v_pk_mul_f32 v[170:171], v[172:173], v[224:225]
	v_mov_b32_e32 v172, v156
	v_mov_b32_e32 v173, v149
	v_mov_b32_e32 v230, v222
	v_pk_mul_f32 v[172:173], v[172:173], v[164:165] op_sel_hi:[1,0]
	v_mov_b32_e32 v222, v68
	v_mov_b32_e32 v223, v73
	v_pk_mul_f32 v[172:173], v[222:223], v[172:173]
	v_mov_b32_e32 v222, v148
	v_mov_b32_e32 v223, v157
	v_pk_mul_f32 v[164:165], v[222:223], v[164:165] op_sel_hi:[1,0]
	v_mov_b32_e32 v222, v72
	v_mov_b32_e32 v223, v69
	v_cndmask_b32_e64 v175, 0, v85, s[6:7]
	v_cndmask_b32_e64 v174, 1.0, v82, s[6:7]
	v_pk_mul_f32 v[164:165], v[222:223], v[164:165]
	v_cndmask_b32_e64 v221, 1.0, v84, s[6:7]
	v_cndmask_b32_e64 v220, 0, v83, s[6:7]
	v_pk_mul_f32 v[222:223], v[174:175], v[164:165]
	v_pk_fma_f32 v[170:171], v[228:229], v[230:231], v[170:171] neg_lo:[0,0,1] neg_hi:[0,0,1]
	v_pk_fma_f32 v[222:223], v[220:221], v[172:173], v[222:223]
	v_mov_b32_e32 v225, v221
	v_mov_b32_e32 v229, v165
	v_mov_b32_e32 v221, v175
	v_mov_b32_e32 v165, v173
	v_mov_b32_e32 v224, v174
	v_mov_b32_e32 v228, v172
	v_pk_mul_f32 v[164:165], v[220:221], v[164:165]
	v_mov_b32_e32 v207, v1
	v_pk_fma_f32 v[172:173], v[224:225], v[228:229], v[164:165] neg_lo:[0,0,1] neg_hi:[0,0,1]
	v_lshlrev_b32_e32 v164, 7, v162
	v_mov_b32_e32 v165, v1
	v_lshl_add_u64 v[164:165], s[10:11], 0, v[164:165]
	v_lshl_add_u64 v[174:175], v[164:165], 0, v[206:207]
	v_cvt_pk_bf16_f32 v164, v166, v167
	v_cvt_pk_bf16_f32 v165, v168, v169
	v_cvt_pk_bf16_f32 v166, v170, v171
	v_cvt_pk_bf16_f32 v167, v172, v173
	global_store_dwordx4 v[174:175], v[164:167], off
	s_mov_b64 s[22:23], 0
	s_nop 0
	v_cvt_pk_bf16_f32 v164, v218, v219
	v_cvt_pk_bf16_f32 v165, v176, v177
	v_cvt_pk_bf16_f32 v166, v226, v227
	v_cvt_pk_bf16_f32 v167, v222, v223
	global_store_dwordx4 v[174:175], v[164:167], off offset:64

; DI u16 f2bf(float a) { return (u16)(pack_bf16(a, 0.f) & 0xffffu); }
;   DI void operator()(const f32x4 (&acc)[2][2][4][2], const Unit& u, int wr, int wc, int fr, int fq) const {
;     ...
;         const int t = u.pm * BM + ai * HALF + wr * 64 + m * 16 + fr;
;         int b, pos;
;         if (rowbase == 0) { b = t >> 12; pos = t & 4095; } else { b = t >> 8; pos = 4096 + (t & 255); }
;         u16* base = qkv + (size_t)(b * 32 + chunk) * LTOT * 64;
;         if (isV) {
; #pragma unroll
;           for (int bj = 0; bj < 2; ++bj)
; #pragma unroll
;             for (int n = 0; n < 2; ++n)
; #pragma unroll
;               for (int e = 0; e < 4; ++e) {
;                 int d = 32 * bj + 8 * fq + 4 * n + e;
;                 base[(size_t)d * LTOT + pos] = f2bf(acc[ai][bj][m][n][e]);
;               }
;         } else {
;           float ss = 0.f;
; #pragma unroll
;           for (int bj = 0; bj < 2; ++bj)
; #pragma unroll
;             for (int n = 0; n < 2; ++n)
; #pragma unroll
;               for (int e = 0; e < 4; ++e) ss += acc[ai][bj][m][n][e] * acc[ai][bj][m][n][e];
;           ss += __shfl_xor(ss, 16);
;           ss += __shfl_xor(ss, 32);
;           const float rinv = rsqrtf(ss * (1.f / 64.f) + EPSV);
;           float o1[8], o2[8];
; #pragma unroll
;           for (int n = 0; n < 2; ++n) {
;             f32x4 cs0 = (f32x4){1.f, 0.f, 1.f, 0.f}, cs1 = cs0;
;             if (ropeT) { cs0 = csr[m & 1][n][0]; cs1 = csr[m & 1][n][1]; }
; #pragma unroll
;             for (int e = 0; e < 4; ++e) {
;               float x1 = acc[ai][0][m][n][e] * (rinv * qs) * g4[0][n][e];
;               float x2 = acc[ai][1][m][n][e] * (rinv * qs) * g4[1][n][e];
;               float c = (e < 2) ? cs0[2 * e] : cs1[2 * (e - 2)], s = (e < 2) ? cs0[2 * e + 1] : cs1[2 * (e - 2) + 1];
;               o1[n * 4 + e] = x1 * c - x2 * s;
;               o2[n * 4 + e] = x2 * c + x1 * s;
;             }
;           }
;           u16* dst = base + (size_t)pos * 64 + 8 * fq;
;           *(uint4*)(dst) = make_uint4(pack_bf16(o1[0], o1[1]), pack_bf16(o1[2], o1[3]), pack_bf16(o1[4], o1[5]), pack_bf16(o1[6], o1[7]));
;           *(uint4*)(dst + 32) = make_uint4(pack_bf16(o2[0], o2[1]), pack_bf16(o2[2], o2[3]), pack_bf16(o2[4], o2[5]), pack_bf16(o2[6], o2[7]));
.LBB0_546:
	s_add_i32 s2, s50, s43
	s_and_b32 s3, s2, 0xfe0
	s_ashr_i32 s2, s2, 7
	s_andn2_b32 s2, s2, 31
	s_add_i32 s2, s2, s48
	v_or_b32_e32 v146, s3, v214
	s_mul_hi_i32 s3, s2, 0x88000
	s_mul_i32 s2, s2, 0x88000
	s_add_u32 s2, s88, s2
	s_addc_u32 s3, s89, s3
	s_and_b64 vcc, exec, s[8:9]
	s_mov_b64 s[22:23], -1
	s_cbranch_vccnz .LBB0_548
	v_mul_f32_e32 v0, v143, v143
	v_fmac_f32_e32 v0, v142, v142
	v_fmac_f32_e32 v0, v144, v144
	v_fmac_f32_e32 v0, v145, v145
	v_fmac_f32_e32 v0, v138, v138
	v_fmac_f32_e32 v0, v139, v139
	v_fmac_f32_e32 v0, v140, v140
	v_fmac_f32_e32 v0, v141, v141
	v_pk_mul_f32 v[150:151], v[134:135], v[134:135]
	v_pk_mul_f32 v[148:149], v[136:137], v[136:137]
	v_add_f32_e32 v0, v150, v0
	v_add_f32_e32 v0, v151, v0
	v_add_f32_e32 v0, v148, v0
	v_add_f32_e32 v0, v149, v0
	v_pk_mul_f32 v[150:151], v[130:131], v[130:131]
	v_pk_mul_f32 v[148:149], v[132:133], v[132:133]
	v_add_f32_e32 v0, v150, v0
	v_add_f32_e32 v0, v151, v0
	v_add_f32_e32 v0, v148, v0
	v_add_f32_e32 v0, v149, v0
	s_mov_b32 s22, 0x800000
	v_mov_b32_e32 v147, v0
	s_nop 1
	v_permlane16_swap_b32_e32 v0, v147
	v_mov_b32_e32 v156, v142
	v_mov_b32_e32 v157, v135
	s_waitcnt vmcnt(0)
	v_mov_b32_e32 v158, v74
	v_mov_b32_e32 v159, v79
	s_waitcnt lgkmcnt(0)
	v_add_f32_e32 v0, v0, v147
	v_mov_b32_e32 v160, v78
	v_mov_b32_e32 v161, v75
	v_mov_b32_e32 v147, v0
	s_nop 1
	v_permlane32_swap_b32_e32 v0, v147
	v_cndmask_b32_e64 v149, 0, v129, s[6:7]
	v_cndmask_b32_e64 v148, 1.0, v126, s[6:7]
	v_cndmask_b32_e64 v151, 1.0, v128, s[6:7]
	v_cndmask_b32_e64 v150, 0, v127, s[6:7]
	s_waitcnt lgkmcnt(0)
	v_add_f32_e32 v0, v0, v147
	v_fmamk_f32 v0, v0, 0x3c800000, v210
	v_mul_f32_e32 v147, 0x4b800000, v0
	v_cmp_gt_f32_e32 vcc, s22, v0
	v_mov_b32_e32 v163, v151
	v_mov_b32_e32 v162, v148
	v_cndmask_b32_e32 v0, v0, v147, vcc
	v_rsq_f32_e32 v0, v0
	v_cndmask_b32_e64 v153, 0, v125, s[6:7]
	v_cndmask_b32_e64 v152, 1.0, v122, s[6:7]
	v_cndmask_b32_e64 v155, 1.0, v124, s[6:7]
	v_mul_f32_e32 v147, 0x45800000, v0
	v_cndmask_b32_e32 v0, v0, v147, vcc
	v_mul_f32_e32 v0, v217, v0
	v_pk_mul_f32 v[156:157], v[156:157], v[0:1] op_sel_hi:[1,0]
	v_cndmask_b32_e64 v154, 0, v123, s[6:7]
	v_pk_mul_f32 v[156:157], v[158:159], v[156:157]
	v_mov_b32_e32 v158, v134
	v_mov_b32_e32 v159, v143
	v_pk_mul_f32 v[158:159], v[158:159], v[0:1] op_sel_hi:[1,0]
	v_mov_b32_e32 v164, v156
	v_pk_mul_f32 v[158:159], v[160:161], v[158:159]
	v_mov_b32_e32 v166, v66
	v_pk_mul_f32 v[160:161], v[148:149], v[158:159]
	v_mov_b32_e32 v165, v159
	v_pk_fma_f32 v[160:161], v[150:151], v[156:157], v[160:161]
	v_mov_b32_e32 v151, v149
	v_mov_b32_e32 v159, v157
	v_pk_mul_f32 v[148:149], v[150:151], v[158:159]
	v_mov_b32_e32 v150, v144
	v_mov_b32_e32 v151, v137
	v_pk_mul_f32 v[150:151], v[150:151], v[0:1] op_sel_hi:[1,0]
	v_mov_b32_e32 v156, v76
	v_mov_b32_e32 v157, v81
	v_pk_mul_f32 v[150:151], v[156:157], v[150:151]
	v_mov_b32_e32 v156, v136
	v_mov_b32_e32 v157, v145
	v_pk_mul_f32 v[156:157], v[156:157], v[0:1] op_sel_hi:[1,0]
	v_mov_b32_e32 v158, v80
	v_mov_b32_e32 v159, v77
	v_pk_mul_f32 v[156:157], v[158:159], v[156:157]
	v_pk_fma_f32 v[148:149], v[162:163], v[164:165], v[148:149] neg_lo:[0,0,1] neg_hi:[0,0,1]
	v_pk_mul_f32 v[158:159], v[152:153], v[156:157]
	v_mov_b32_e32 v163, v155
	v_pk_fma_f32 v[158:159], v[154:155], v[150:151], v[158:159]
	v_mov_b32_e32 v165, v157
	v_mov_b32_e32 v155, v153
	v_mov_b32_e32 v157, v151
	v_mov_b32_e32 v162, v152
	v_mov_b32_e32 v164, v150
	v_pk_mul_f32 v[150:151], v[154:155], v[156:157]
	v_mov_b32_e32 v167, v71
	v_pk_fma_f32 v[150:151], v[162:163], v[164:165], v[150:151] neg_lo:[0,0,1] neg_hi:[0,0,1]
	v_mov_b32_e32 v164, v138
	v_mov_b32_e32 v165, v131
	v_pk_mul_f32 v[164:165], v[164:165], v[0:1] op_sel_hi:[1,0]
	v_mov_b32_e32 v168, v70
	v_pk_mul_f32 v[164:165], v[166:167], v[164:165]
	v_mov_b32_e32 v166, v130
	v_mov_b32_e32 v167, v139
	v_pk_mul_f32 v[166:167], v[166:167], v[0:1] op_sel_hi:[1,0]
	v_mov_b32_e32 v169, v67
	v_cndmask_b32_e64 v153, 0, v121, s[6:7]
	v_cndmask_b32_e64 v152, 1.0, v118, s[6:7]
	v_pk_mul_f32 v[166:167], v[168:169], v[166:167]
	v_cndmask_b32_e64 v155, 1.0, v120, s[6:7]
	v_cndmask_b32_e64 v154, 0, v119, s[6:7]
	v_pk_mul_f32 v[168:169], v[152:153], v[166:167]
	v_mov_b32_e32 v171, v155
	v_pk_fma_f32 v[168:169], v[154:155], v[164:165], v[168:169]
	v_mov_b32_e32 v173, v167
	v_mov_b32_e32 v155, v153
	v_mov_b32_e32 v167, v165
	v_mov_b32_e32 v170, v152
	v_pk_mul_f32 v[152:153], v[154:155], v[166:167]
	v_mov_b32_e32 v154, v140
	v_mov_b32_e32 v155, v133
	v_mov_b32_e32 v172, v164
	v_pk_mul_f32 v[154:155], v[154:155], v[0:1] op_sel_hi:[1,0]
	v_mov_b32_e32 v164, v68
	v_mov_b32_e32 v165, v73
	v_pk_mul_f32 v[154:155], v[164:165], v[154:155]
	v_mov_b32_e32 v164, v132
	v_mov_b32_e32 v165, v141
	v_pk_mul_f32 v[164:165], v[164:165], v[0:1] op_sel_hi:[1,0]
	v_mov_b32_e32 v166, v72
	v_mov_b32_e32 v167, v69
	v_cndmask_b32_e64 v157, 0, v117, s[6:7]
	v_cndmask_b32_e64 v156, 1.0, v114, s[6:7]
	v_pk_mul_f32 v[164:165], v[166:167], v[164:165]
	v_cndmask_b32_e64 v163, 1.0, v116, s[6:7]
	v_cndmask_b32_e64 v162, 0, v115, s[6:7]
	v_pk_mul_f32 v[166:167], v[156:157], v[164:165]
	v_pk_fma_f32 v[152:153], v[170:171], v[172:173], v[152:153] neg_lo:[0,0,1] neg_hi:[0,0,1]
	v_pk_fma_f32 v[166:167], v[162:163], v[154:155], v[166:167]
	v_mov_b32_e32 v171, v163
	v_mov_b32_e32 v173, v165
	v_mov_b32_e32 v163, v157
	v_mov_b32_e32 v165, v155
	v_mov_b32_e32 v170, v156
	v_mov_b32_e32 v172, v154
	v_pk_mul_f32 v[154:155], v[162:163], v[164:165]
	v_lshlrev_b32_e32 v0, 7, v146
	v_pk_fma_f32 v[154:155], v[170:171], v[172:173], v[154:155] neg_lo:[0,0,1] neg_hi:[0,0,1]
	v_lshl_add_u64 v[156:157], s[2:3], 0, v[0:1]
	v_mov_b32_e32 v207, v1
	v_lshl_add_u64 v[156:157], v[156:157], 0, v[206:207]
	v_cvt_pk_bf16_f32 v148, v148, v149
	v_cvt_pk_bf16_f32 v149, v150, v151
	v_cvt_pk_bf16_f32 v150, v152, v153
	v_cvt_pk_bf16_f32 v151, v154, v155
	global_store_dwordx4 v[156:157], v[148:151], off
	s_mov_b64 s[22:23], 0
	s_nop 0
	v_cvt_pk_bf16_f32 v148, v160, v161
	v_cvt_pk_bf16_f32 v149, v158, v159
	v_cvt_pk_bf16_f32 v150, v168, v169
	v_cvt_pk_bf16_f32 v151, v166, v167
	global_store_dwordx4 v[156:157], v[148:151], off offset:64

; DI u16 f2bf(float a) { return (u16)(pack_bf16(a, 0.f) & 0xffffu); }
;   DI void operator()(const f32x4 (&acc)[2][2][4][2], const Unit& u, int wr, int wc, int fr, int fq) const {
;     ...
;         const int t = u.pm * BM + ai * HALF + wr * 64 + m * 16 + fr;
;         int b, pos;
;         if (rowbase == 0) { b = t >> 12; pos = t & 4095; } else { b = t >> 8; pos = 4096 + (t & 255); }
;         u16* base = qkv + (size_t)(b * 32 + chunk) * LTOT * 64;
;         if (isV) {
; #pragma unroll
;           for (int bj = 0; bj < 2; ++bj)
; #pragma unroll
;             for (int n = 0; n < 2; ++n)
; #pragma unroll
;               for (int e = 0; e < 4; ++e) {
;                 int d = 32 * bj + 8 * fq + 4 * n + e;
;                 base[(size_t)d * LTOT + pos] = f2bf(acc[ai][bj][m][n][e]);
;               }
;         } else {
;           float ss = 0.f;
; #pragma unroll
;           for (int bj = 0; bj < 2; ++bj)
; #pragma unroll
;             for (int n = 0; n < 2; ++n)
; #pragma unroll
;               for (int e = 0; e < 4; ++e) ss += acc[ai][bj][m][n][e] * acc[ai][bj][m][n][e];
;           ss += __shfl_xor(ss, 16);
;           ss += __shfl_xor(ss, 32);
;           const float rinv = rsqrtf(ss * (1.f / 64.f) + EPSV);
;           float o1[8], o2[8];
; #pragma unroll
;           for (int n = 0; n < 2; ++n) {
;             f32x4 cs0 = (f32x4){1.f, 0.f, 1.f, 0.f}, cs1 = cs0;
;             if (ropeT) { cs0 = csr[m & 1][n][0]; cs1 = csr[m & 1][n][1]; }
; #pragma unroll
;             for (int e = 0; e < 4; ++e) {
;               float x1 = acc[ai][0][m][n][e] * (rinv * qs) * g4[0][n][e];
;               float x2 = acc[ai][1][m][n][e] * (rinv * qs) * g4[1][n][e];
;               float c = (e < 2) ? cs0[2 * e] : cs1[2 * (e - 2)], s = (e < 2) ? cs0[2 * e + 1] : cs1[2 * (e - 2) + 1];
;               o1[n * 4 + e] = x1 * c - x2 * s;
;               o2[n * 4 + e] = x2 * c + x1 * s;
;             }
;           }
;           u16* dst = base + (size_t)pos * 64 + 8 * fq;
;           *(uint4*)(dst) = make_uint4(pack_bf16(o1[0], o1[1]), pack_bf16(o1[2], o1[3]), pack_bf16(o1[4], o1[5]), pack_bf16(o1[6], o1[7]));
;           *(uint4*)(dst + 32) = make_uint4(pack_bf16(o2[0], o2[1]), pack_bf16(o2[2], o2[3]), pack_bf16(o2[4], o2[5]), pack_bf16(o2[6], o2[7]));
.LBB0_550:
	s_add_i32 s50, s50, s44
	s_and_b32 s2, s50, 0xff0
	v_or_b32_e32 v130, s2, v214
	s_ashr_i32 s2, s50, 7
	s_andn2_b32 s2, s2, 31
	s_add_i32 s2, s2, s48
	s_mul_hi_i32 s3, s2, 0x88000
	s_mul_i32 s2, s2, 0x88000
	s_add_u32 s2, s88, s2
	s_addc_u32 s3, s89, s3
	s_and_b64 vcc, exec, s[8:9]
	s_mov_b64 s[22:23], -1
	s_cbranch_vccnz .LBB0_552
	v_mul_f32_e32 v0, v111, v111
	v_fmac_f32_e32 v0, v110, v110
	v_fmac_f32_e32 v0, v112, v112
	v_fmac_f32_e32 v0, v113, v113
	v_fmac_f32_e32 v0, v106, v106
	v_fmac_f32_e32 v0, v107, v107
	v_fmac_f32_e32 v0, v108, v108
	v_fmac_f32_e32 v0, v109, v109
	v_pk_mul_f32 v[134:135], v[102:103], v[102:103]
	v_pk_mul_f32 v[132:133], v[104:105], v[104:105]
	v_add_f32_e32 v0, v134, v0
	v_add_f32_e32 v0, v135, v0
	v_add_f32_e32 v0, v132, v0
	v_add_f32_e32 v0, v133, v0
	v_pk_mul_f32 v[134:135], v[90:91], v[90:91]
	v_pk_mul_f32 v[132:133], v[92:93], v[92:93]
	v_add_f32_e32 v0, v134, v0
	v_add_f32_e32 v0, v135, v0
	v_add_f32_e32 v0, v132, v0
	v_add_f32_e32 v0, v133, v0
	s_mov_b32 s22, 0x800000
	v_mov_b32_e32 v131, v0
	s_nop 1
	v_permlane16_swap_b32_e32 v0, v131
	v_mov_b32_e32 v140, v110
	v_mov_b32_e32 v141, v103
	v_mov_b32_e32 v142, v74
	v_mov_b32_e32 v143, v79
	s_waitcnt lgkmcnt(0)
	v_add_f32_e32 v0, v0, v131
	v_mov_b32_e32 v144, v78
	v_mov_b32_e32 v145, v75
	v_mov_b32_e32 v131, v0
	s_nop 1
	v_permlane32_swap_b32_e32 v0, v131
	v_cndmask_b32_e64 v133, 0, v97, s[6:7]
	v_cndmask_b32_e64 v132, 1.0, v94, s[6:7]
	v_cndmask_b32_e64 v135, 1.0, v96, s[6:7]
	v_cndmask_b32_e64 v134, 0, v95, s[6:7]
	s_waitcnt lgkmcnt(0)
	v_add_f32_e32 v0, v0, v131
	v_fmamk_f32 v0, v0, 0x3c800000, v210
	v_mul_f32_e32 v131, 0x4b800000, v0
	v_cmp_gt_f32_e32 vcc, s22, v0
	v_mov_b32_e32 v147, v135
	v_mov_b32_e32 v146, v132
	v_cndmask_b32_e32 v0, v0, v131, vcc
	v_rsq_f32_e32 v0, v0
	v_cndmask_b32_e64 v137, 0, v101, s[6:7]
	v_cndmask_b32_e64 v136, 1.0, v98, s[6:7]
	v_cndmask_b32_e64 v139, 1.0, v100, s[6:7]
	v_mul_f32_e32 v131, 0x45800000, v0
	v_cndmask_b32_e32 v0, v0, v131, vcc
	v_mul_f32_e32 v0, v217, v0
	v_pk_mul_f32 v[140:141], v[140:141], v[0:1] op_sel_hi:[1,0]
	v_cndmask_b32_e64 v138, 0, v99, s[6:7]
	v_pk_mul_f32 v[140:141], v[142:143], v[140:141]
	v_mov_b32_e32 v142, v102
	v_mov_b32_e32 v143, v111
	v_pk_mul_f32 v[142:143], v[142:143], v[0:1] op_sel_hi:[1,0]
	v_mov_b32_e32 v148, v140
	v_pk_mul_f32 v[142:143], v[144:145], v[142:143]
	v_mov_b32_e32 v150, v66
	v_pk_mul_f32 v[144:145], v[132:133], v[142:143]
	v_mov_b32_e32 v149, v143
	v_pk_fma_f32 v[144:145], v[134:135], v[140:141], v[144:145]
	v_mov_b32_e32 v135, v133
	v_mov_b32_e32 v143, v141
	v_pk_mul_f32 v[132:133], v[134:135], v[142:143]
	v_mov_b32_e32 v134, v112
	v_mov_b32_e32 v135, v105
	v_pk_mul_f32 v[134:135], v[134:135], v[0:1] op_sel_hi:[1,0]
	v_mov_b32_e32 v140, v76
	v_mov_b32_e32 v141, v81
	v_pk_mul_f32 v[134:135], v[140:141], v[134:135]
	v_mov_b32_e32 v140, v104
	v_mov_b32_e32 v141, v113
	v_pk_mul_f32 v[140:141], v[140:141], v[0:1] op_sel_hi:[1,0]
	v_mov_b32_e32 v142, v80
	v_mov_b32_e32 v143, v77
	v_pk_mul_f32 v[140:141], v[142:143], v[140:141]
	v_pk_fma_f32 v[132:133], v[146:147], v[148:149], v[132:133] neg_lo:[0,0,1] neg_hi:[0,0,1]
	v_pk_mul_f32 v[142:143], v[136:137], v[140:141]
	v_mov_b32_e32 v147, v139
	v_pk_fma_f32 v[142:143], v[138:139], v[134:135], v[142:143]
	v_mov_b32_e32 v149, v141
	v_mov_b32_e32 v139, v137
	v_mov_b32_e32 v141, v135
	v_mov_b32_e32 v146, v136
	v_mov_b32_e32 v148, v134
	v_pk_mul_f32 v[134:135], v[138:139], v[140:141]
	v_mov_b32_e32 v151, v71
	v_pk_fma_f32 v[134:135], v[146:147], v[148:149], v[134:135] neg_lo:[0,0,1] neg_hi:[0,0,1]
	v_mov_b32_e32 v148, v106
	v_mov_b32_e32 v149, v91
	v_pk_mul_f32 v[148:149], v[148:149], v[0:1] op_sel_hi:[1,0]
	v_mov_b32_e32 v152, v70
	v_pk_mul_f32 v[148:149], v[150:151], v[148:149]
	v_mov_b32_e32 v150, v90
	v_mov_b32_e32 v151, v107
	v_pk_mul_f32 v[150:151], v[150:151], v[0:1] op_sel_hi:[1,0]
	v_mov_b32_e32 v153, v67
	v_cndmask_b32_e64 v137, 0, v89, s[6:7]
	v_cndmask_b32_e64 v136, 1.0, v86, s[6:7]
	v_pk_mul_f32 v[150:151], v[152:153], v[150:151]
	v_cndmask_b32_e64 v139, 1.0, v88, s[6:7]
	v_cndmask_b32_e64 v138, 0, v87, s[6:7]
	v_pk_mul_f32 v[152:153], v[136:137], v[150:151]
	v_mov_b32_e32 v155, v139
	v_pk_fma_f32 v[152:153], v[138:139], v[148:149], v[152:153]
	v_mov_b32_e32 v157, v151
	v_mov_b32_e32 v139, v137
	v_mov_b32_e32 v151, v149
	v_mov_b32_e32 v154, v136
	v_pk_mul_f32 v[136:137], v[138:139], v[150:151]
	v_mov_b32_e32 v138, v108
	v_mov_b32_e32 v139, v93
	v_mov_b32_e32 v156, v148
	v_pk_mul_f32 v[138:139], v[138:139], v[0:1] op_sel_hi:[1,0]
	v_mov_b32_e32 v148, v68
	v_mov_b32_e32 v149, v73
	v_pk_mul_f32 v[138:139], v[148:149], v[138:139]
	v_mov_b32_e32 v148, v92
	v_mov_b32_e32 v149, v109
	v_pk_mul_f32 v[148:149], v[148:149], v[0:1] op_sel_hi:[1,0]
	v_mov_b32_e32 v150, v72
	v_mov_b32_e32 v151, v69
	v_cndmask_b32_e64 v141, 0, v85, s[6:7]
	v_cndmask_b32_e64 v140, 1.0, v82, s[6:7]
	v_pk_mul_f32 v[148:149], v[150:151], v[148:149]
	v_cndmask_b32_e64 v147, 1.0, v84, s[6:7]
	v_cndmask_b32_e64 v146, 0, v83, s[6:7]
	v_pk_mul_f32 v[150:151], v[140:141], v[148:149]
	v_pk_fma_f32 v[136:137], v[154:155], v[156:157], v[136:137] neg_lo:[0,0,1] neg_hi:[0,0,1]
	v_pk_fma_f32 v[150:151], v[146:147], v[138:139], v[150:151]
	v_mov_b32_e32 v155, v147
	v_mov_b32_e32 v157, v149
	v_mov_b32_e32 v147, v141
	v_mov_b32_e32 v149, v139
	v_mov_b32_e32 v154, v140
	v_mov_b32_e32 v156, v138
	v_pk_mul_f32 v[138:139], v[146:147], v[148:149]
	v_lshlrev_b32_e32 v0, 7, v130
	v_pk_fma_f32 v[138:139], v[154:155], v[156:157], v[138:139] neg_lo:[0,0,1] neg_hi:[0,0,1]
	v_lshl_add_u64 v[140:141], s[2:3], 0, v[0:1]
	v_mov_b32_e32 v207, v1
	v_lshl_add_u64 v[140:141], v[140:141], 0, v[206:207]
	v_cvt_pk_bf16_f32 v132, v132, v133
	v_cvt_pk_bf16_f32 v133, v134, v135
	v_cvt_pk_bf16_f32 v134, v136, v137
	v_cvt_pk_bf16_f32 v135, v138, v139
	global_store_dwordx4 v[140:141], v[132:135], off
	s_mov_b64 s[22:23], 0
	s_nop 0
	v_cvt_pk_bf16_f32 v132, v144, v145
	v_cvt_pk_bf16_f32 v133, v142, v143
	v_cvt_pk_bf16_f32 v134, v152, v153
	v_cvt_pk_bf16_f32 v135, v150, v151
	global_store_dwordx4 v[140:141], v[132:135], off offset:64

; DI u16 f2bf(float a) { return (u16)(pack_bf16(a, 0.f) & 0xffffu); }
;   DI void operator()(const f32x4 (&acc)[2][2][4][2], const Unit& u, int wr, int wc, int fr, int fq) const {
;     ...
;         const int t = u.pm * BM + ai * HALF + wr * 64 + m * 16 + fr;
;         int b, pos;
;         if (rowbase == 0) { b = t >> 12; pos = t & 4095; } else { b = t >> 8; pos = 4096 + (t & 255); }
;         u16* base = qkv + (size_t)(b * 32 + chunk) * LTOT * 64;
;         if (isV) {
; #pragma unroll
;           for (int bj = 0; bj < 2; ++bj)
; #pragma unroll
;             for (int n = 0; n < 2; ++n)
; #pragma unroll
;               for (int e = 0; e < 4; ++e) {
;                 int d = 32 * bj + 8 * fq + 4 * n + e;
;                 base[(size_t)d * LTOT + pos] = f2bf(acc[ai][bj][m][n][e]);
;               }
;         } else {
;           float ss = 0.f;
; #pragma unroll
;           for (int bj = 0; bj < 2; ++bj)
; #pragma unroll
;             for (int n = 0; n < 2; ++n)
; #pragma unroll
;               for (int e = 0; e < 4; ++e) ss += acc[ai][bj][m][n][e] * acc[ai][bj][m][n][e];
;           ss += __shfl_xor(ss, 16);
;           ss += __shfl_xor(ss, 32);
;           const float rinv = rsqrtf(ss * (1.f / 64.f) + EPSV);
;           float o1[8], o2[8];
; #pragma unroll
;           for (int n = 0; n < 2; ++n) {
;             f32x4 cs0 = (f32x4){1.f, 0.f, 1.f, 0.f}, cs1 = cs0;
;             if (ropeT) { cs0 = csr[m & 1][n][0]; cs1 = csr[m & 1][n][1]; }
; #pragma unroll
;             for (int e = 0; e < 4; ++e) {
;               float x1 = acc[ai][0][m][n][e] * (rinv * qs) * g4[0][n][e];
;               float x2 = acc[ai][1][m][n][e] * (rinv * qs) * g4[1][n][e];
;               float c = (e < 2) ? cs0[2 * e] : cs1[2 * (e - 2)], s = (e < 2) ? cs0[2 * e + 1] : cs1[2 * (e - 2) + 1];
;               o1[n * 4 + e] = x1 * c - x2 * s;
;               o2[n * 4 + e] = x2 * c + x1 * s;
;             }
;           }
;           u16* dst = base + (size_t)pos * 64 + 8 * fq;
;           *(uint4*)(dst) = make_uint4(pack_bf16(o1[0], o1[1]), pack_bf16(o1[2], o1[3]), pack_bf16(o1[4], o1[5]), pack_bf16(o1[6], o1[7]));
;           *(uint4*)(dst + 32) = make_uint4(pack_bf16(o2[0], o2[1]), pack_bf16(o2[2], o2[3]), pack_bf16(o2[4], o2[5]), pack_bf16(o2[6], o2[7]));
.LBB0_556:
	s_ashr_i32 s2, s2, 7
	s_andn2_b32 s2, s2, 31
	s_add_i32 s2, s2, s48
	s_mul_hi_i32 s3, s2, 0x88000
	s_mul_i32 s2, s2, 0x88000
	s_add_u32 s2, s88, s2
	s_addc_u32 s3, s89, s3
	s_and_b64 vcc, exec, s[8:9]
	s_mov_b64 s[22:23], -1
	s_cbranch_vccnz .LBB0_558
	v_mul_f32_e32 v91, v63, v63
	v_fmac_f32_e32 v91, v62, v62
	v_fmac_f32_e32 v91, v64, v64
	v_fmac_f32_e32 v91, v65, v65
	v_fmac_f32_e32 v91, v58, v58
	v_fmac_f32_e32 v91, v59, v59
	v_fmac_f32_e32 v91, v60, v60
	v_fmac_f32_e32 v91, v61, v61
	v_pk_mul_f32 v[102:103], v[54:55], v[54:55]
	v_pk_mul_f32 v[92:93], v[56:57], v[56:57]
	v_add_f32_e32 v91, v102, v91
	v_add_f32_e32 v91, v103, v91
	v_add_f32_e32 v91, v92, v91
	v_add_f32_e32 v91, v93, v91
	v_pk_mul_f32 v[102:103], v[50:51], v[50:51]
	v_pk_mul_f32 v[92:93], v[52:53], v[52:53]
	v_add_f32_e32 v91, v102, v91
	v_add_f32_e32 v91, v103, v91
	v_add_f32_e32 v91, v92, v91
	v_add_f32_e32 v91, v93, v91
	s_mov_b32 s22, 0x800000
	v_mov_b32_e32 v110, v62
	v_mov_b32_e32 v92, v91
	s_nop 1
	v_permlane16_swap_b32_e32 v91, v92
	v_mov_b32_e32 v111, v55
	s_waitcnt vmcnt(0)
	v_mov_b32_e32 v112, v74
	v_mov_b32_e32 v113, v79
	v_mov_b32_e32 v130, v78
	s_waitcnt lgkmcnt(0)
	v_add_f32_e32 v91, v91, v92
	v_mov_b32_e32 v131, v75
	v_cndmask_b32_e64 v103, 0, v129, s[6:7]
	v_mov_b32_e32 v92, v91
	s_nop 1
	v_permlane32_swap_b32_e32 v91, v92
	v_cndmask_b32_e64 v102, 1.0, v126, s[6:7]
	v_cndmask_b32_e64 v105, 1.0, v128, s[6:7]
	v_cndmask_b32_e64 v104, 0, v127, s[6:7]
	v_mov_b32_e32 v133, v105
	s_waitcnt lgkmcnt(0)
	v_add_f32_e32 v91, v91, v92
	v_fmamk_f32 v91, v91, 0x3c800000, v210
	v_mul_f32_e32 v92, 0x4b800000, v91
	v_cmp_gt_f32_e32 vcc, s22, v91
	v_mov_b32_e32 v132, v102
	v_cndmask_b32_e64 v107, 0, v125, s[6:7]
	v_cndmask_b32_e32 v91, v91, v92, vcc
	v_rsq_f32_e32 v91, v91
	v_cndmask_b32_e64 v106, 1.0, v122, s[6:7]
	v_cndmask_b32_e64 v109, 1.0, v124, s[6:7]
	v_cndmask_b32_e64 v108, 0, v123, s[6:7]
	v_mul_f32_e32 v92, 0x45800000, v91
	v_cndmask_b32_e32 v91, v91, v92, vcc
	v_mul_f32_e32 v92, v217, v91
	v_pk_mul_f32 v[110:111], v[110:111], v[92:93] op_sel_hi:[1,0]
	v_mov_b32_e32 v136, v66
	v_pk_mul_f32 v[110:111], v[112:113], v[110:111]
	v_mov_b32_e32 v112, v54
	v_mov_b32_e32 v113, v63
	v_pk_mul_f32 v[112:113], v[112:113], v[92:93] op_sel_hi:[1,0]
	v_mov_b32_e32 v134, v110
	v_pk_mul_f32 v[112:113], v[130:131], v[112:113]
	v_mov_b32_e32 v137, v71
	v_pk_mul_f32 v[130:131], v[102:103], v[112:113]
	v_mov_b32_e32 v135, v113
	v_pk_fma_f32 v[130:131], v[104:105], v[110:111], v[130:131]
	v_mov_b32_e32 v105, v103
	v_mov_b32_e32 v113, v111
	v_pk_mul_f32 v[102:103], v[104:105], v[112:113]
	v_mov_b32_e32 v104, v64
	v_mov_b32_e32 v105, v57
	v_pk_mul_f32 v[104:105], v[104:105], v[92:93] op_sel_hi:[1,0]
	v_mov_b32_e32 v110, v76
	v_mov_b32_e32 v111, v81
	v_pk_mul_f32 v[104:105], v[110:111], v[104:105]
	v_mov_b32_e32 v110, v56
	v_mov_b32_e32 v111, v65
	v_pk_mul_f32 v[110:111], v[110:111], v[92:93] op_sel_hi:[1,0]
	v_mov_b32_e32 v112, v80
	v_mov_b32_e32 v113, v77
	v_pk_mul_f32 v[110:111], v[112:113], v[110:111]
	v_pk_fma_f32 v[102:103], v[132:133], v[134:135], v[102:103] neg_lo:[0,0,1] neg_hi:[0,0,1]
	v_pk_mul_f32 v[112:113], v[106:107], v[110:111]
	v_mov_b32_e32 v133, v109
	v_pk_fma_f32 v[112:113], v[108:109], v[104:105], v[112:113]
	v_mov_b32_e32 v135, v111
	v_mov_b32_e32 v109, v107
	v_mov_b32_e32 v111, v105
	v_mov_b32_e32 v132, v106
	v_mov_b32_e32 v134, v104
	v_pk_mul_f32 v[104:105], v[108:109], v[110:111]
	v_mov_b32_e32 v138, v70
	v_pk_fma_f32 v[104:105], v[132:133], v[134:135], v[104:105] neg_lo:[0,0,1] neg_hi:[0,0,1]
	v_mov_b32_e32 v134, v58
	v_mov_b32_e32 v135, v51
	v_pk_mul_f32 v[134:135], v[134:135], v[92:93] op_sel_hi:[1,0]
	v_mov_b32_e32 v139, v67
	v_pk_mul_f32 v[134:135], v[136:137], v[134:135]
	v_mov_b32_e32 v136, v50
	v_mov_b32_e32 v137, v59
	v_pk_mul_f32 v[136:137], v[136:137], v[92:93] op_sel_hi:[1,0]
	v_cndmask_b32_e64 v107, 0, v121, s[6:7]
	v_cndmask_b32_e64 v106, 1.0, v118, s[6:7]
	v_pk_mul_f32 v[136:137], v[138:139], v[136:137]
	v_cndmask_b32_e64 v109, 1.0, v120, s[6:7]
	v_cndmask_b32_e64 v108, 0, v119, s[6:7]
	v_pk_mul_f32 v[138:139], v[106:107], v[136:137]
	v_mov_b32_e32 v141, v109
	v_pk_fma_f32 v[138:139], v[108:109], v[134:135], v[138:139]
	v_mov_b32_e32 v143, v137
	v_mov_b32_e32 v109, v107
	v_mov_b32_e32 v137, v135
	v_mov_b32_e32 v140, v106
	v_pk_mul_f32 v[106:107], v[108:109], v[136:137]
	v_mov_b32_e32 v108, v60
	v_mov_b32_e32 v109, v53
	v_mov_b32_e32 v142, v134
	v_pk_mul_f32 v[108:109], v[108:109], v[92:93] op_sel_hi:[1,0]
	v_mov_b32_e32 v134, v68
	v_mov_b32_e32 v135, v73
	v_pk_mul_f32 v[108:109], v[134:135], v[108:109]
	v_mov_b32_e32 v134, v52
	v_mov_b32_e32 v135, v61
	v_pk_mul_f32 v[92:93], v[134:135], v[92:93] op_sel_hi:[1,0]
	v_mov_b32_e32 v134, v72
	v_mov_b32_e32 v135, v69
	v_cndmask_b32_e64 v111, 0, v117, s[6:7]
	v_cndmask_b32_e64 v110, 1.0, v114, s[6:7]
	v_pk_mul_f32 v[92:93], v[134:135], v[92:93]
	v_cndmask_b32_e64 v133, 1.0, v116, s[6:7]
	v_cndmask_b32_e64 v132, 0, v115, s[6:7]
	v_pk_mul_f32 v[134:135], v[110:111], v[92:93]
	v_pk_fma_f32 v[106:107], v[140:141], v[142:143], v[106:107] neg_lo:[0,0,1] neg_hi:[0,0,1]
	v_pk_fma_f32 v[134:135], v[132:133], v[108:109], v[134:135]
	v_mov_b32_e32 v137, v133
	v_mov_b32_e32 v141, v93
	v_mov_b32_e32 v133, v111
	v_mov_b32_e32 v93, v109
	v_mov_b32_e32 v136, v110
	v_mov_b32_e32 v140, v108
	v_pk_mul_f32 v[92:93], v[132:133], v[92:93]
	v_lshlrev_b32_e32 v108, 7, v90
	v_mov_b32_e32 v109, v1
	v_pk_fma_f32 v[92:93], v[136:137], v[140:141], v[92:93] neg_lo:[0,0,1] neg_hi:[0,0,1]
	v_lshl_add_u64 v[108:109], s[2:3], 0, v[108:109]
	v_mov_b32_e32 v207, v1
	v_lshl_add_u64 v[108:109], v[108:109], 0, v[206:207]
	v_cvt_pk_bf16_f32 v102, v102, v103
	v_cvt_pk_bf16_f32 v103, v104, v105
	v_cvt_pk_bf16_f32 v104, v106, v107
	v_cvt_pk_bf16_f32 v105, v92, v93
	global_store_dwordx4 v[108:109], v[102:105], off
	s_mov_b64 s[22:23], 0
	s_nop 0
	v_cvt_pk_bf16_f32 v102, v130, v131
	v_cvt_pk_bf16_f32 v103, v112, v113
	v_cvt_pk_bf16_f32 v104, v138, v139
	v_cvt_pk_bf16_f32 v105, v134, v135
	global_store_dwordx4 v[108:109], v[102:105], off offset:64

; DI u16 f2bf(float a) { return (u16)(pack_bf16(a, 0.f) & 0xffffu); }
;   DI void operator()(const f32x4 (&acc)[2][2][4][2], const Unit& u, int wr, int wc, int fr, int fq) const {
;     ...
;         const int t = u.pm * BM + ai * HALF + wr * 64 + m * 16 + fr;
;         int b, pos;
;         if (rowbase == 0) { b = t >> 12; pos = t & 4095; } else { b = t >> 8; pos = 4096 + (t & 255); }
;         u16* base = qkv + (size_t)(b * 32 + chunk) * LTOT * 64;
;         if (isV) {
; #pragma unroll
;           for (int bj = 0; bj < 2; ++bj)
; #pragma unroll
;             for (int n = 0; n < 2; ++n)
; #pragma unroll
;               for (int e = 0; e < 4; ++e) {
;                 int d = 32 * bj + 8 * fq + 4 * n + e;
;                 base[(size_t)d * LTOT + pos] = f2bf(acc[ai][bj][m][n][e]);
;               }
;         } else {
;           float ss = 0.f;
; #pragma unroll
;           for (int bj = 0; bj < 2; ++bj)
; #pragma unroll
;             for (int n = 0; n < 2; ++n)
; #pragma unroll
;               for (int e = 0; e < 4; ++e) ss += acc[ai][bj][m][n][e] * acc[ai][bj][m][n][e];
;           ss += __shfl_xor(ss, 16);
;           ss += __shfl_xor(ss, 32);
;           const float rinv = rsqrtf(ss * (1.f / 64.f) + EPSV);
;           float o1[8], o2[8];
; #pragma unroll
;           for (int n = 0; n < 2; ++n) {
;             f32x4 cs0 = (f32x4){1.f, 0.f, 1.f, 0.f}, cs1 = cs0;
;             if (ropeT) { cs0 = csr[m & 1][n][0]; cs1 = csr[m & 1][n][1]; }
; #pragma unroll
;             for (int e = 0; e < 4; ++e) {
;               float x1 = acc[ai][0][m][n][e] * (rinv * qs) * g4[0][n][e];
;               float x2 = acc[ai][1][m][n][e] * (rinv * qs) * g4[1][n][e];
;               float c = (e < 2) ? cs0[2 * e] : cs1[2 * (e - 2)], s = (e < 2) ? cs0[2 * e + 1] : cs1[2 * (e - 2) + 1];
;               o1[n * 4 + e] = x1 * c - x2 * s;
;               o2[n * 4 + e] = x2 * c + x1 * s;
;             }
;           }
;           u16* dst = base + (size_t)pos * 64 + 8 * fq;
;           *(uint4*)(dst) = make_uint4(pack_bf16(o1[0], o1[1]), pack_bf16(o1[2], o1[3]), pack_bf16(o1[4], o1[5]), pack_bf16(o1[6], o1[7]));
;           *(uint4*)(dst + 32) = make_uint4(pack_bf16(o2[0], o2[1]), pack_bf16(o2[2], o2[3]), pack_bf16(o2[4], o2[5]), pack_bf16(o2[6], o2[7]));
.LBB0_560:
	s_add_i32 s2, s49, 0x90
	s_and_b32 s3, s2, 0xfd0
	s_ashr_i32 s2, s2, 7
	s_andn2_b32 s2, s2, 31
	s_add_i32 s2, s2, s48
	v_or_b32_e32 v50, s3, v214
	s_mul_hi_i32 s3, s2, 0x88000
	s_mul_i32 s2, s2, 0x88000
	s_add_u32 s2, s88, s2
	s_addc_u32 s3, s89, s3
	s_and_b64 vcc, exec, s[8:9]
	s_mov_b64 s[22:23], -1
	s_cbranch_vccnz .LBB0_572
	v_mul_f32_e32 v51, v47, v47
	v_fmac_f32_e32 v51, v46, v46
	v_fmac_f32_e32 v51, v48, v48
	v_fmac_f32_e32 v51, v49, v49
	v_fmac_f32_e32 v51, v42, v42
	v_fmac_f32_e32 v51, v43, v43
	v_fmac_f32_e32 v51, v44, v44
	v_fmac_f32_e32 v51, v45, v45
	v_pk_mul_f32 v[54:55], v[38:39], v[38:39]
	v_pk_mul_f32 v[52:53], v[40:41], v[40:41]
	v_add_f32_e32 v51, v54, v51
	v_add_f32_e32 v51, v55, v51
	v_add_f32_e32 v51, v52, v51
	v_add_f32_e32 v51, v53, v51
	v_pk_mul_f32 v[54:55], v[34:35], v[34:35]
	v_pk_mul_f32 v[52:53], v[36:37], v[36:37]
	v_add_f32_e32 v51, v54, v51
	v_add_f32_e32 v51, v55, v51
	v_add_f32_e32 v51, v52, v51
	v_add_f32_e32 v51, v53, v51
	s_mov_b32 s22, 0x800000
	v_mov_b32_e32 v62, v46
	v_mov_b32_e32 v52, v51
	s_nop 1
	v_permlane16_swap_b32_e32 v51, v52
	v_mov_b32_e32 v63, v39
	v_mov_b32_e32 v64, v74
	v_mov_b32_e32 v65, v79
	v_mov_b32_e32 v90, v78
	s_waitcnt lgkmcnt(0)
	v_add_f32_e32 v51, v51, v52
	v_mov_b32_e32 v91, v75
	v_cndmask_b32_e64 v55, 0, v97, s[6:7]
	v_mov_b32_e32 v52, v51
	s_nop 1
	v_permlane32_swap_b32_e32 v51, v52
	v_cndmask_b32_e64 v54, 1.0, v94, s[6:7]
	v_cndmask_b32_e64 v57, 1.0, v96, s[6:7]
	v_cndmask_b32_e64 v56, 0, v95, s[6:7]
	v_mov_b32_e32 v93, v57
	s_waitcnt lgkmcnt(0)
	v_add_f32_e32 v51, v51, v52
	v_fmamk_f32 v51, v51, 0x3c800000, v210
	v_mul_f32_e32 v52, 0x4b800000, v51
	v_cmp_gt_f32_e32 vcc, s22, v51
	v_mov_b32_e32 v92, v54
	v_cndmask_b32_e64 v59, 0, v101, s[6:7]
	v_cndmask_b32_e32 v51, v51, v52, vcc
	v_rsq_f32_e32 v51, v51
	v_cndmask_b32_e64 v58, 1.0, v98, s[6:7]
	v_cndmask_b32_e64 v61, 1.0, v100, s[6:7]
	v_cndmask_b32_e64 v60, 0, v99, s[6:7]
	v_mul_f32_e32 v52, 0x45800000, v51
	v_cndmask_b32_e32 v51, v51, v52, vcc
	v_mul_f32_e32 v52, v217, v51
	v_pk_mul_f32 v[62:63], v[62:63], v[52:53] op_sel_hi:[1,0]
	v_mov_b32_e32 v104, v66
	v_pk_mul_f32 v[62:63], v[64:65], v[62:63]
	v_mov_b32_e32 v64, v38
	v_mov_b32_e32 v65, v47
	v_pk_mul_f32 v[64:65], v[64:65], v[52:53] op_sel_hi:[1,0]
	v_mov_b32_e32 v102, v62
	v_pk_mul_f32 v[64:65], v[90:91], v[64:65]
	v_mov_b32_e32 v105, v71
	v_pk_mul_f32 v[90:91], v[54:55], v[64:65]
	v_mov_b32_e32 v103, v65
	v_pk_fma_f32 v[90:91], v[56:57], v[62:63], v[90:91]
	v_mov_b32_e32 v57, v55
	v_mov_b32_e32 v65, v63
	v_pk_mul_f32 v[54:55], v[56:57], v[64:65]
	v_mov_b32_e32 v56, v48
	v_mov_b32_e32 v57, v41
	v_pk_mul_f32 v[56:57], v[56:57], v[52:53] op_sel_hi:[1,0]
	v_mov_b32_e32 v62, v76
	v_mov_b32_e32 v63, v81
	v_pk_mul_f32 v[56:57], v[62:63], v[56:57]
	v_mov_b32_e32 v62, v40
	v_mov_b32_e32 v63, v49
	v_pk_mul_f32 v[62:63], v[62:63], v[52:53] op_sel_hi:[1,0]
	v_mov_b32_e32 v64, v80
	v_mov_b32_e32 v65, v77
	v_pk_mul_f32 v[62:63], v[64:65], v[62:63]
	v_pk_fma_f32 v[54:55], v[92:93], v[102:103], v[54:55] neg_lo:[0,0,1] neg_hi:[0,0,1]
	v_pk_mul_f32 v[64:65], v[58:59], v[62:63]
	v_mov_b32_e32 v93, v61
	v_pk_fma_f32 v[64:65], v[60:61], v[56:57], v[64:65]
	v_mov_b32_e32 v103, v63
	v_mov_b32_e32 v61, v59
	v_mov_b32_e32 v63, v57
	v_mov_b32_e32 v92, v58
	v_mov_b32_e32 v102, v56
	v_pk_mul_f32 v[56:57], v[60:61], v[62:63]
	v_mov_b32_e32 v106, v70
	v_pk_fma_f32 v[56:57], v[92:93], v[102:103], v[56:57] neg_lo:[0,0,1] neg_hi:[0,0,1]
	v_mov_b32_e32 v102, v42
	v_mov_b32_e32 v103, v35
	v_pk_mul_f32 v[102:103], v[102:103], v[52:53] op_sel_hi:[1,0]
	v_mov_b32_e32 v107, v67
	v_pk_mul_f32 v[102:103], v[104:105], v[102:103]
	v_mov_b32_e32 v104, v34
	v_mov_b32_e32 v105, v43
	v_pk_mul_f32 v[104:105], v[104:105], v[52:53] op_sel_hi:[1,0]
	v_cndmask_b32_e64 v59, 0, v89, s[6:7]
	v_cndmask_b32_e64 v58, 1.0, v86, s[6:7]
	v_pk_mul_f32 v[104:105], v[106:107], v[104:105]
	v_cndmask_b32_e64 v61, 1.0, v88, s[6:7]
	v_cndmask_b32_e64 v60, 0, v87, s[6:7]
	v_pk_mul_f32 v[106:107], v[58:59], v[104:105]
	v_mov_b32_e32 v109, v61
	v_pk_fma_f32 v[106:107], v[60:61], v[102:103], v[106:107]
	v_mov_b32_e32 v111, v105
	v_mov_b32_e32 v61, v59
	v_mov_b32_e32 v105, v103
	v_mov_b32_e32 v108, v58
	v_pk_mul_f32 v[58:59], v[60:61], v[104:105]
	v_mov_b32_e32 v60, v44
	v_mov_b32_e32 v61, v37
	v_mov_b32_e32 v110, v102
	v_pk_mul_f32 v[60:61], v[60:61], v[52:53] op_sel_hi:[1,0]
	v_mov_b32_e32 v102, v68
	v_mov_b32_e32 v103, v73
	v_pk_mul_f32 v[60:61], v[102:103], v[60:61]
	v_mov_b32_e32 v102, v36
	v_mov_b32_e32 v103, v45
	v_pk_mul_f32 v[52:53], v[102:103], v[52:53] op_sel_hi:[1,0]
	v_mov_b32_e32 v102, v72
	v_mov_b32_e32 v103, v69
	v_cndmask_b32_e64 v63, 0, v85, s[6:7]
	v_cndmask_b32_e64 v62, 1.0, v82, s[6:7]
	v_pk_mul_f32 v[52:53], v[102:103], v[52:53]
	v_cndmask_b32_e64 v93, 1.0, v84, s[6:7]
	v_cndmask_b32_e64 v92, 0, v83, s[6:7]
	v_pk_mul_f32 v[102:103], v[62:63], v[52:53]
	v_pk_fma_f32 v[58:59], v[108:109], v[110:111], v[58:59] neg_lo:[0,0,1] neg_hi:[0,0,1]
	v_pk_fma_f32 v[102:103], v[92:93], v[60:61], v[102:103]
	v_mov_b32_e32 v105, v93
	v_mov_b32_e32 v109, v53
	v_mov_b32_e32 v93, v63
	v_mov_b32_e32 v53, v61
	v_mov_b32_e32 v104, v62
	v_mov_b32_e32 v108, v60
	v_pk_mul_f32 v[52:53], v[92:93], v[52:53]
	v_mov_b32_e32 v207, v1
	v_pk_fma_f32 v[60:61], v[104:105], v[108:109], v[52:53] neg_lo:[0,0,1] neg_hi:[0,0,1]
	v_lshlrev_b32_e32 v52, 7, v50
	v_mov_b32_e32 v53, v1
	v_lshl_add_u64 v[52:53], s[2:3], 0, v[52:53]
	v_lshl_add_u64 v[62:63], v[52:53], 0, v[206:207]
	v_cvt_pk_bf16_f32 v52, v54, v55
	v_cvt_pk_bf16_f32 v53, v56, v57
	v_cvt_pk_bf16_f32 v54, v58, v59
	v_cvt_pk_bf16_f32 v55, v60, v61
	global_store_dwordx4 v[62:63], v[52:55], off
	s_nop 1
	v_cvt_pk_bf16_f32 v52, v90, v91
	v_cvt_pk_bf16_f32 v53, v64, v65
	v_cvt_pk_bf16_f32 v54, v106, v107
	v_cvt_pk_bf16_f32 v55, v102, v103
	global_store_dwordx4 v[62:63], v[52:55], off offset:64
	s_cbranch_execz .LBB0_573

; DI u16 f2bf(float a) { return (u16)(pack_bf16(a, 0.f) & 0xffffu); }
;   DI void operator()(const f32x4 (&acc)[2][2][4][2], const Unit& u, int wr, int wc, int fr, int fq) const {
;     ...
;         const int t = u.pm * BM + ai * HALF + wr * 64 + m * 16 + fr;
;         int b, pos;
;         if (rowbase == 0) { b = t >> 12; pos = t & 4095; } else { b = t >> 8; pos = 4096 + (t & 255); }
;         u16* base = qkv + (size_t)(b * 32 + chunk) * LTOT * 64;
;         if (isV) {
; #pragma unroll
;           for (int bj = 0; bj < 2; ++bj)
; #pragma unroll
;             for (int n = 0; n < 2; ++n)
; #pragma unroll
;               for (int e = 0; e < 4; ++e) {
;                 int d = 32 * bj + 8 * fq + 4 * n + e;
;                 base[(size_t)d * LTOT + pos] = f2bf(acc[ai][bj][m][n][e]);
;               }
;         } else {
;           float ss = 0.f;
; #pragma unroll
;           for (int bj = 0; bj < 2; ++bj)
; #pragma unroll
;             for (int n = 0; n < 2; ++n)
; #pragma unroll
;               for (int e = 0; e < 4; ++e) ss += acc[ai][bj][m][n][e] * acc[ai][bj][m][n][e];
;           ss += __shfl_xor(ss, 16);
;           ss += __shfl_xor(ss, 32);
;           const float rinv = rsqrtf(ss * (1.f / 64.f) + EPSV);
;           float o1[8], o2[8];
; #pragma unroll
;           for (int n = 0; n < 2; ++n) {
;             f32x4 cs0 = (f32x4){1.f, 0.f, 1.f, 0.f}, cs1 = cs0;
;             if (ropeT) { cs0 = csr[m & 1][n][0]; cs1 = csr[m & 1][n][1]; }
; #pragma unroll
;             for (int e = 0; e < 4; ++e) {
;               float x1 = acc[ai][0][m][n][e] * (rinv * qs) * g4[0][n][e];
;               float x2 = acc[ai][1][m][n][e] * (rinv * qs) * g4[1][n][e];
;               float c = (e < 2) ? cs0[2 * e] : cs1[2 * (e - 2)], s = (e < 2) ? cs0[2 * e + 1] : cs1[2 * (e - 2) + 1];
;               o1[n * 4 + e] = x1 * c - x2 * s;
;               o2[n * 4 + e] = x2 * c + x1 * s;
;             }
;           }
;           u16* dst = base + (size_t)pos * 64 + 8 * fq;
;           *(uint4*)(dst) = make_uint4(pack_bf16(o1[0], o1[1]), pack_bf16(o1[2], o1[3]), pack_bf16(o1[4], o1[5]), pack_bf16(o1[6], o1[7]));
;           *(uint4*)(dst + 32) = make_uint4(pack_bf16(o2[0], o2[1]), pack_bf16(o2[2], o2[3]), pack_bf16(o2[4], o2[5]), pack_bf16(o2[6], o2[7]));
.LBB0_564:
	s_add_i32 s2, s49, 0xa0
	s_and_b32 s3, s2, 0xfe0
	s_ashr_i32 s2, s2, 7
	s_andn2_b32 s2, s2, 31
	s_add_i32 s2, s2, s48
	v_or_b32_e32 v34, s3, v214
	s_mul_hi_i32 s3, s2, 0x88000
	s_mul_i32 s2, s2, 0x88000
	s_add_u32 s2, s88, s2
	s_addc_u32 s3, s89, s3
	s_and_b64 vcc, exec, s[8:9]
	s_mov_b64 s[10:11], -1
	s_cbranch_vccnz .LBB0_566
	v_mul_f32_e32 v0, v31, v31
	v_fmac_f32_e32 v0, v30, v30
	v_fmac_f32_e32 v0, v32, v32
	v_fmac_f32_e32 v0, v33, v33
	v_fmac_f32_e32 v0, v26, v26
	v_fmac_f32_e32 v0, v27, v27
	v_fmac_f32_e32 v0, v28, v28
	v_fmac_f32_e32 v0, v29, v29
	v_pk_mul_f32 v[38:39], v[22:23], v[22:23]
	v_pk_mul_f32 v[36:37], v[24:25], v[24:25]
	v_add_f32_e32 v0, v38, v0
	v_add_f32_e32 v0, v39, v0
	v_add_f32_e32 v0, v36, v0
	v_add_f32_e32 v0, v37, v0
	v_pk_mul_f32 v[38:39], v[18:19], v[18:19]
	v_pk_mul_f32 v[36:37], v[20:21], v[20:21]
	v_add_f32_e32 v0, v38, v0
	v_add_f32_e32 v0, v39, v0
	v_add_f32_e32 v0, v36, v0
	v_add_f32_e32 v0, v37, v0
	s_mov_b32 s10, 0x800000
	v_mov_b32_e32 v35, v0
	s_nop 1
	v_permlane16_swap_b32_e32 v0, v35
	v_mov_b32_e32 v44, v30
	v_mov_b32_e32 v45, v23
	s_waitcnt vmcnt(0)
	v_mov_b32_e32 v46, v74
	v_mov_b32_e32 v47, v79
	s_waitcnt lgkmcnt(0)
	v_add_f32_e32 v0, v0, v35
	v_mov_b32_e32 v48, v78
	v_mov_b32_e32 v49, v75
	v_mov_b32_e32 v35, v0
	s_nop 1
	v_permlane32_swap_b32_e32 v0, v35
	v_cndmask_b32_e64 v37, 0, v129, s[6:7]
	v_cndmask_b32_e64 v36, 1.0, v126, s[6:7]
	v_cndmask_b32_e64 v39, 1.0, v128, s[6:7]
	v_cndmask_b32_e64 v38, 0, v127, s[6:7]
	s_waitcnt lgkmcnt(0)
	v_add_f32_e32 v0, v0, v35
	v_fmamk_f32 v0, v0, 0x3c800000, v210
	v_mul_f32_e32 v35, 0x4b800000, v0
	v_cmp_gt_f32_e32 vcc, s10, v0
	v_mov_b32_e32 v51, v39
	v_mov_b32_e32 v50, v36
	v_cndmask_b32_e32 v0, v0, v35, vcc
	v_rsq_f32_e32 v0, v0
	v_cndmask_b32_e64 v41, 0, v125, s[6:7]
	v_cndmask_b32_e64 v40, 1.0, v122, s[6:7]
	v_cndmask_b32_e64 v43, 1.0, v124, s[6:7]
	v_mul_f32_e32 v35, 0x45800000, v0
	v_cndmask_b32_e32 v0, v0, v35, vcc
	v_mul_f32_e32 v0, v217, v0
	v_pk_mul_f32 v[44:45], v[44:45], v[0:1] op_sel_hi:[1,0]
	v_cndmask_b32_e64 v42, 0, v123, s[6:7]
	v_pk_mul_f32 v[44:45], v[46:47], v[44:45]
	v_mov_b32_e32 v46, v22
	v_mov_b32_e32 v47, v31
	v_pk_mul_f32 v[46:47], v[46:47], v[0:1] op_sel_hi:[1,0]
	v_mov_b32_e32 v52, v44
	v_pk_mul_f32 v[46:47], v[48:49], v[46:47]
	v_mov_b32_e32 v54, v66
	v_pk_mul_f32 v[48:49], v[36:37], v[46:47]
	v_mov_b32_e32 v53, v47
	v_pk_fma_f32 v[48:49], v[38:39], v[44:45], v[48:49]
	v_mov_b32_e32 v39, v37
	v_mov_b32_e32 v47, v45
	v_pk_mul_f32 v[36:37], v[38:39], v[46:47]
	v_mov_b32_e32 v38, v32
	v_mov_b32_e32 v39, v25
	v_pk_mul_f32 v[38:39], v[38:39], v[0:1] op_sel_hi:[1,0]
	v_mov_b32_e32 v44, v76
	v_mov_b32_e32 v45, v81
	v_pk_mul_f32 v[38:39], v[44:45], v[38:39]
	v_mov_b32_e32 v44, v24
	v_mov_b32_e32 v45, v33
	v_pk_mul_f32 v[44:45], v[44:45], v[0:1] op_sel_hi:[1,0]
	v_mov_b32_e32 v46, v80
	v_mov_b32_e32 v47, v77
	v_pk_mul_f32 v[44:45], v[46:47], v[44:45]
	v_pk_fma_f32 v[36:37], v[50:51], v[52:53], v[36:37] neg_lo:[0,0,1] neg_hi:[0,0,1]
	v_pk_mul_f32 v[46:47], v[40:41], v[44:45]
	v_mov_b32_e32 v51, v43
	v_pk_fma_f32 v[46:47], v[42:43], v[38:39], v[46:47]
	v_mov_b32_e32 v53, v45
	v_mov_b32_e32 v43, v41
	v_mov_b32_e32 v45, v39
	v_mov_b32_e32 v50, v40
	v_mov_b32_e32 v52, v38
	v_pk_mul_f32 v[38:39], v[42:43], v[44:45]
	v_mov_b32_e32 v55, v71
	v_pk_fma_f32 v[38:39], v[50:51], v[52:53], v[38:39] neg_lo:[0,0,1] neg_hi:[0,0,1]
	v_mov_b32_e32 v52, v26
	v_mov_b32_e32 v53, v19
	v_pk_mul_f32 v[52:53], v[52:53], v[0:1] op_sel_hi:[1,0]
	v_mov_b32_e32 v56, v70
	v_pk_mul_f32 v[52:53], v[54:55], v[52:53]
	v_mov_b32_e32 v54, v18
	v_mov_b32_e32 v55, v27
	v_pk_mul_f32 v[54:55], v[54:55], v[0:1] op_sel_hi:[1,0]
	v_mov_b32_e32 v57, v67
	v_cndmask_b32_e64 v41, 0, v121, s[6:7]
	v_cndmask_b32_e64 v40, 1.0, v118, s[6:7]
	v_pk_mul_f32 v[54:55], v[56:57], v[54:55]
	v_cndmask_b32_e64 v43, 1.0, v120, s[6:7]
	v_cndmask_b32_e64 v42, 0, v119, s[6:7]
	v_pk_mul_f32 v[56:57], v[40:41], v[54:55]
	v_mov_b32_e32 v59, v43
	v_pk_fma_f32 v[56:57], v[42:43], v[52:53], v[56:57]
	v_mov_b32_e32 v61, v55
	v_mov_b32_e32 v43, v41
	v_mov_b32_e32 v55, v53
	v_mov_b32_e32 v58, v40
	v_pk_mul_f32 v[40:41], v[42:43], v[54:55]
	v_mov_b32_e32 v42, v28
	v_mov_b32_e32 v43, v21
	v_mov_b32_e32 v60, v52
	v_pk_mul_f32 v[42:43], v[42:43], v[0:1] op_sel_hi:[1,0]
	v_mov_b32_e32 v52, v68
	v_mov_b32_e32 v53, v73
	v_pk_mul_f32 v[42:43], v[52:53], v[42:43]
	v_mov_b32_e32 v52, v20
	v_mov_b32_e32 v53, v29
	v_pk_mul_f32 v[52:53], v[52:53], v[0:1] op_sel_hi:[1,0]
	v_mov_b32_e32 v54, v72
	v_mov_b32_e32 v55, v69
	v_cndmask_b32_e64 v45, 0, v117, s[6:7]
	v_cndmask_b32_e64 v44, 1.0, v114, s[6:7]
	v_pk_mul_f32 v[52:53], v[54:55], v[52:53]
	v_cndmask_b32_e64 v51, 1.0, v116, s[6:7]
	v_cndmask_b32_e64 v50, 0, v115, s[6:7]
	v_pk_mul_f32 v[54:55], v[44:45], v[52:53]
	v_pk_fma_f32 v[40:41], v[58:59], v[60:61], v[40:41] neg_lo:[0,0,1] neg_hi:[0,0,1]
	v_pk_fma_f32 v[54:55], v[50:51], v[42:43], v[54:55]
	v_mov_b32_e32 v59, v51
	v_mov_b32_e32 v61, v53
	v_mov_b32_e32 v51, v45
	v_mov_b32_e32 v53, v43
	v_mov_b32_e32 v58, v44
	v_mov_b32_e32 v60, v42
	v_pk_mul_f32 v[42:43], v[50:51], v[52:53]
	v_lshlrev_b32_e32 v0, 7, v34
	v_pk_fma_f32 v[42:43], v[58:59], v[60:61], v[42:43] neg_lo:[0,0,1] neg_hi:[0,0,1]
	v_lshl_add_u64 v[44:45], s[2:3], 0, v[0:1]
	v_mov_b32_e32 v207, v1
	v_lshl_add_u64 v[44:45], v[44:45], 0, v[206:207]
	v_cvt_pk_bf16_f32 v36, v36, v37
	v_cvt_pk_bf16_f32 v37, v38, v39
	v_cvt_pk_bf16_f32 v38, v40, v41
	v_cvt_pk_bf16_f32 v39, v42, v43
	global_store_dwordx4 v[44:45], v[36:39], off
	s_mov_b64 s[10:11], 0
	s_nop 0
	v_cvt_pk_bf16_f32 v36, v48, v49
	v_cvt_pk_bf16_f32 v37, v46, v47
	v_cvt_pk_bf16_f32 v38, v56, v57
	v_cvt_pk_bf16_f32 v39, v54, v55
	global_store_dwordx4 v[44:45], v[36:39], off offset:64

; DI u16 f2bf(float a) { return (u16)(pack_bf16(a, 0.f) & 0xffffu); }
;   DI void operator()(const f32x4 (&acc)[2][2][4][2], const Unit& u, int wr, int wc, int fr, int fq) const {
;     ...
;         const int t = u.pm * BM + ai * HALF + wr * 64 + m * 16 + fr;
;         int b, pos;
;         if (rowbase == 0) { b = t >> 12; pos = t & 4095; } else { b = t >> 8; pos = 4096 + (t & 255); }
;         u16* base = qkv + (size_t)(b * 32 + chunk) * LTOT * 64;
;         if (isV) {
; #pragma unroll
;           for (int bj = 0; bj < 2; ++bj)
; #pragma unroll
;             for (int n = 0; n < 2; ++n)
; #pragma unroll
;               for (int e = 0; e < 4; ++e) {
;                 int d = 32 * bj + 8 * fq + 4 * n + e;
;                 base[(size_t)d * LTOT + pos] = f2bf(acc[ai][bj][m][n][e]);
;               }
;         } else {
;           float ss = 0.f;
; #pragma unroll
;           for (int bj = 0; bj < 2; ++bj)
; #pragma unroll
;             for (int n = 0; n < 2; ++n)
; #pragma unroll
;               for (int e = 0; e < 4; ++e) ss += acc[ai][bj][m][n][e] * acc[ai][bj][m][n][e];
;           ss += __shfl_xor(ss, 16);
;           ss += __shfl_xor(ss, 32);
;           const float rinv = rsqrtf(ss * (1.f / 64.f) + EPSV);
;           float o1[8], o2[8];
; #pragma unroll
;           for (int n = 0; n < 2; ++n) {
;             f32x4 cs0 = (f32x4){1.f, 0.f, 1.f, 0.f}, cs1 = cs0;
;             if (ropeT) { cs0 = csr[m & 1][n][0]; cs1 = csr[m & 1][n][1]; }
; #pragma unroll
;             for (int e = 0; e < 4; ++e) {
;               float x1 = acc[ai][0][m][n][e] * (rinv * qs) * g4[0][n][e];
;               float x2 = acc[ai][1][m][n][e] * (rinv * qs) * g4[1][n][e];
;               float c = (e < 2) ? cs0[2 * e] : cs1[2 * (e - 2)], s = (e < 2) ? cs0[2 * e + 1] : cs1[2 * (e - 2) + 1];
;               o1[n * 4 + e] = x1 * c - x2 * s;
;               o2[n * 4 + e] = x2 * c + x1 * s;
;             }
;           }
;           u16* dst = base + (size_t)pos * 64 + 8 * fq;
;           *(uint4*)(dst) = make_uint4(pack_bf16(o1[0], o1[1]), pack_bf16(o1[2], o1[3]), pack_bf16(o1[4], o1[5]), pack_bf16(o1[6], o1[7]));
;           *(uint4*)(dst + 32) = make_uint4(pack_bf16(o2[0], o2[1]), pack_bf16(o2[2], o2[3]), pack_bf16(o2[4], o2[5]), pack_bf16(o2[6], o2[7]));
.LBB0_568:
	s_addk_i32 s49, 0xb0
	s_and_b32 s2, s49, 0xff0
	v_or_b32_e32 v18, s2, v214
	s_ashr_i32 s2, s49, 7
	s_andn2_b32 s2, s2, 31
	s_add_i32 s2, s2, s48
	s_mul_hi_i32 s3, s2, 0x88000
	s_mul_i32 s2, s2, 0x88000
	s_add_u32 s2, s88, s2
	s_addc_u32 s3, s89, s3
	s_and_b64 vcc, exec, s[8:9]
	s_mov_b64 s[8:9], -1
	s_cbranch_vccnz .LBB0_570
	v_mul_f32_e32 v0, v15, v15
	v_fmac_f32_e32 v0, v14, v14
	v_fmac_f32_e32 v0, v16, v16
	v_fmac_f32_e32 v0, v17, v17
	v_fmac_f32_e32 v0, v10, v10
	v_fmac_f32_e32 v0, v11, v11
	v_fmac_f32_e32 v0, v12, v12
	v_fmac_f32_e32 v0, v13, v13
	v_pk_mul_f32 v[22:23], v[6:7], v[6:7]
	v_pk_mul_f32 v[20:21], v[8:9], v[8:9]
	v_add_f32_e32 v0, v22, v0
	v_add_f32_e32 v0, v23, v0
	v_add_f32_e32 v0, v20, v0
	v_add_f32_e32 v0, v21, v0
	v_pk_mul_f32 v[22:23], v[2:3], v[2:3]
	v_pk_mul_f32 v[20:21], v[4:5], v[4:5]
	v_add_f32_e32 v0, v22, v0
	v_add_f32_e32 v0, v23, v0
	v_add_f32_e32 v0, v20, v0
	v_add_f32_e32 v0, v21, v0
	s_mov_b32 s8, 0x800000
	v_mov_b32_e32 v19, v0
	s_nop 1
	v_permlane16_swap_b32_e32 v0, v19
	v_mov_b32_e32 v28, v14
	v_mov_b32_e32 v29, v7
	v_mov_b32_e32 v30, v74
	v_mov_b32_e32 v31, v79
	s_waitcnt lgkmcnt(0)
	v_add_f32_e32 v0, v0, v19
	v_mov_b32_e32 v79, v75
	v_cndmask_b32_e64 v21, 0, v97, s[6:7]
	v_mov_b32_e32 v19, v0
	s_nop 1
	v_permlane32_swap_b32_e32 v0, v19
	v_cndmask_b32_e64 v20, 1.0, v94, s[6:7]
	v_cndmask_b32_e64 v23, 1.0, v96, s[6:7]
	v_cndmask_b32_e64 v22, 0, v95, s[6:7]
	v_mov_b32_e32 v35, v23
	s_waitcnt lgkmcnt(0)
	v_add_f32_e32 v0, v0, v19
	v_fmamk_f32 v0, v0, 0x3c800000, v210
	v_mul_f32_e32 v19, 0x4b800000, v0
	v_cmp_gt_f32_e32 vcc, s8, v0
	v_mov_b32_e32 v34, v20
	v_cndmask_b32_e64 v25, 0, v101, s[6:7]
	v_cndmask_b32_e32 v0, v0, v19, vcc
	v_rsq_f32_e32 v0, v0
	v_cndmask_b32_e64 v24, 1.0, v98, s[6:7]
	v_cndmask_b32_e64 v27, 1.0, v100, s[6:7]
	v_cndmask_b32_e64 v26, 0, v99, s[6:7]
	v_mul_f32_e32 v19, 0x45800000, v0
	v_cndmask_b32_e32 v0, v0, v19, vcc
	v_mul_f32_e32 v0, v217, v0
	v_pk_mul_f32 v[28:29], v[28:29], v[0:1] op_sel_hi:[1,0]
	v_mov_b32_e32 v38, v66
	v_pk_mul_f32 v[28:29], v[30:31], v[28:29]
	v_mov_b32_e32 v30, v6
	v_mov_b32_e32 v31, v15
	v_pk_mul_f32 v[30:31], v[30:31], v[0:1] op_sel_hi:[1,0]
	v_mov_b32_e32 v36, v28
	v_pk_mul_f32 v[30:31], v[78:79], v[30:31]
	v_mov_b32_e32 v39, v71
	v_pk_mul_f32 v[32:33], v[20:21], v[30:31]
	v_mov_b32_e32 v37, v31
	v_pk_fma_f32 v[32:33], v[22:23], v[28:29], v[32:33]
	v_mov_b32_e32 v23, v21
	v_mov_b32_e32 v31, v29
	v_pk_mul_f32 v[20:21], v[22:23], v[30:31]
	v_mov_b32_e32 v22, v16
	v_mov_b32_e32 v23, v9
	v_pk_mul_f32 v[22:23], v[22:23], v[0:1] op_sel_hi:[1,0]
	v_mov_b32_e32 v28, v76
	v_mov_b32_e32 v29, v81
	v_pk_mul_f32 v[22:23], v[28:29], v[22:23]
	v_mov_b32_e32 v28, v8
	v_mov_b32_e32 v29, v17
	v_pk_mul_f32 v[28:29], v[28:29], v[0:1] op_sel_hi:[1,0]
	v_mov_b32_e32 v81, v77
	v_pk_mul_f32 v[28:29], v[80:81], v[28:29]
	v_pk_fma_f32 v[20:21], v[34:35], v[36:37], v[20:21] neg_lo:[0,0,1] neg_hi:[0,0,1]
	v_pk_mul_f32 v[30:31], v[24:25], v[28:29]
	v_mov_b32_e32 v35, v27
	v_pk_fma_f32 v[30:31], v[26:27], v[22:23], v[30:31]
	v_mov_b32_e32 v37, v29
	v_mov_b32_e32 v27, v25
	v_mov_b32_e32 v29, v23
	v_mov_b32_e32 v34, v24
	v_mov_b32_e32 v36, v22
	v_pk_mul_f32 v[22:23], v[26:27], v[28:29]
	v_mov_b32_e32 v71, v67
	v_pk_fma_f32 v[22:23], v[34:35], v[36:37], v[22:23] neg_lo:[0,0,1] neg_hi:[0,0,1]
	v_mov_b32_e32 v36, v10
	v_mov_b32_e32 v37, v3
	v_pk_mul_f32 v[36:37], v[36:37], v[0:1] op_sel_hi:[1,0]
	v_cndmask_b32_e64 v25, 0, v89, s[6:7]
	v_pk_mul_f32 v[36:37], v[38:39], v[36:37]
	v_mov_b32_e32 v38, v2
	v_mov_b32_e32 v39, v11
	v_pk_mul_f32 v[38:39], v[38:39], v[0:1] op_sel_hi:[1,0]
	v_cndmask_b32_e64 v24, 1.0, v86, s[6:7]
	v_pk_mul_f32 v[38:39], v[70:71], v[38:39]
	v_cndmask_b32_e64 v27, 1.0, v88, s[6:7]
	v_cndmask_b32_e64 v26, 0, v87, s[6:7]
	v_pk_mul_f32 v[40:41], v[24:25], v[38:39]
	v_mov_b32_e32 v43, v27
	v_pk_fma_f32 v[40:41], v[26:27], v[36:37], v[40:41]
	v_mov_b32_e32 v45, v39
	v_mov_b32_e32 v27, v25
	v_mov_b32_e32 v39, v37
	v_mov_b32_e32 v42, v24
	v_pk_mul_f32 v[24:25], v[26:27], v[38:39]
	v_mov_b32_e32 v26, v12
	v_mov_b32_e32 v27, v5
	v_mov_b32_e32 v44, v36
	v_pk_mul_f32 v[26:27], v[26:27], v[0:1] op_sel_hi:[1,0]
	v_mov_b32_e32 v36, v68
	v_mov_b32_e32 v37, v73
	v_pk_mul_f32 v[26:27], v[36:37], v[26:27]
	v_mov_b32_e32 v36, v4
	v_mov_b32_e32 v37, v13
	v_pk_mul_f32 v[36:37], v[36:37], v[0:1] op_sel_hi:[1,0]
	v_mov_b32_e32 v73, v69
	v_cndmask_b32_e64 v29, 0, v85, s[6:7]
	v_cndmask_b32_e64 v28, 1.0, v82, s[6:7]
	v_pk_mul_f32 v[36:37], v[72:73], v[36:37]
	v_cndmask_b32_e64 v35, 1.0, v84, s[6:7]
	v_cndmask_b32_e64 v34, 0, v83, s[6:7]
	v_pk_mul_f32 v[38:39], v[28:29], v[36:37]
	v_pk_fma_f32 v[24:25], v[42:43], v[44:45], v[24:25] neg_lo:[0,0,1] neg_hi:[0,0,1]
	v_pk_fma_f32 v[38:39], v[34:35], v[26:27], v[38:39]
	v_mov_b32_e32 v43, v35
	v_mov_b32_e32 v45, v37
	v_mov_b32_e32 v35, v29
	v_mov_b32_e32 v37, v27
	v_mov_b32_e32 v42, v28
	v_mov_b32_e32 v44, v26
	v_pk_mul_f32 v[26:27], v[34:35], v[36:37]
	v_lshlrev_b32_e32 v0, 7, v18
	v_pk_fma_f32 v[26:27], v[42:43], v[44:45], v[26:27] neg_lo:[0,0,1] neg_hi:[0,0,1]
	v_lshl_add_u64 v[28:29], s[2:3], 0, v[0:1]
	v_mov_b32_e32 v207, v1
	v_lshl_add_u64 v[28:29], v[28:29], 0, v[206:207]
	v_cvt_pk_bf16_f32 v20, v20, v21
	v_cvt_pk_bf16_f32 v21, v22, v23
	v_cvt_pk_bf16_f32 v22, v24, v25
	v_cvt_pk_bf16_f32 v23, v26, v27
	global_store_dwordx4 v[28:29], v[20:23], off
	s_mov_b64 s[8:9], 0
	s_nop 0
	v_cvt_pk_bf16_f32 v20, v32, v33
	v_cvt_pk_bf16_f32 v21, v30, v31
	v_cvt_pk_bf16_f32 v22, v40, v41
	v_cvt_pk_bf16_f32 v23, v38, v39
	global_store_dwordx4 v[28:29], v[20:23], off offset:64

;   DI void operator()(const f32x4 (&acc)[2][2][4][2], const Unit& u, int wr, int wc, int fr, int fq) const {
;     ...
;     f32x4 g4[2][2];
; #pragma unroll
;     for (int bj = 0; bj < 2; ++bj)
; #pragma unroll
;       for (int n = 0; n < 2; ++n) g4[bj][n] = *(const f32x4*)(gam + 32 * bj + 8 * fq + 4 * n);
;     ...
;         const int t = u.pm * BM + ai * HALF + wr * 64 + m * 16 + fr;
;         int b, pos;
;         if (rowbase == 0) { b = t >> 12; pos = t & 4095; } else { b = t >> 8; pos = 4096 + (t & 255); }
;         u16* base = qkv + (size_t)(b * 32 + chunk) * LTOT * 64;
;         if (isV) {
; #pragma unroll
;           for (int bj = 0; bj < 2; ++bj)
; #pragma unroll
;             for (int n = 0; n < 2; ++n)
; #pragma unroll
;               for (int e = 0; e < 4; ++e) {
;                 int d = 32 * bj + 8 * fq + 4 * n + e;
;                 base[(size_t)d * LTOT + pos] = f2bf(acc[ai][bj][m][n][e]);
;               }
;         } else {
;           float ss = 0.f;
; #pragma unroll
;           for (int bj = 0; bj < 2; ++bj)
; #pragma unroll
;             for (int n = 0; n < 2; ++n)
; #pragma unroll
;               for (int e = 0; e < 4; ++e) ss += acc[ai][bj][m][n][e] * acc[ai][bj][m][n][e];
;           ss += __shfl_xor(ss, 16);
;           ss += __shfl_xor(ss, 32);
;           const float rinv = rsqrtf(ss * (1.f / 64.f) + EPSV);
;           float o1[8], o2[8];
; #pragma unroll
;           for (int n = 0; n < 2; ++n) {
;             f32x4 cs0 = (f32x4){1.f, 0.f, 1.f, 0.f}, cs1 = cs0;
;             if (ropeT) { cs0 = csr[m & 1][n][0]; cs1 = csr[m & 1][n][1]; }
; #pragma unroll
;             for (int e = 0; e < 4; ++e) {
;               float x1 = acc[ai][0][m][n][e] * (rinv * qs) * g4[0][n][e];
;               float x2 = acc[ai][1][m][n][e] * (rinv * qs) * g4[1][n][e];
;               float c = (e < 2) ? cs0[2 * e] : cs1[2 * (e - 2)], s = (e < 2) ? cs0[2 * e + 1] : cs1[2 * (e - 2) + 1];
;               o1[n * 4 + e] = x1 * c - x2 * s;
;               o2[n * 4 + e] = x2 * c + x1 * s;
;             }
;           }
;           u16* dst = base + (size_t)pos * 64 + 8 * fq;
;           *(uint4*)(dst) = make_uint4(pack_bf16(o1[0], o1[1]), pack_bf16(o1[2], o1[3]), pack_bf16(o1[4], o1[5]), pack_bf16(o1[6], o1[7]));
;           *(uint4*)(dst + 32) = make_uint4(pack_bf16(o2[0], o2[1]), pack_bf16(o2[2], o2[3]), pack_bf16(o2[4], o2[5]), pack_bf16(o2[6], o2[7]));
.LBB0_841:
	v_readlane_b32 s7, v254, 39
	v_readlane_b32 s16, v252, 0
	s_mulk_i32 s7, 0x600
	v_readlane_b32 s18, v252, 2
	v_readlane_b32 s19, v252, 3
	s_add_u32 s7, s18, s7
	s_addc_u32 s9, s19, 0
	s_lshl_b32 s6, s6, 2
	s_add_u32 s6, s7, s6
	s_addc_u32 s7, s9, 0
	v_lshlrev_b32_e32 v0, 5, v148
	global_load_dwordx4 v[82:85], v0, s[6:7] offset:16
	global_load_dwordx4 v[90:93], v0, s[6:7]
	global_load_dwordx4 v[86:89], v0, s[6:7] offset:144
	global_load_dwordx4 v[94:97], v0, s[6:7] offset:128
	s_or_b64 vcc, s[0:1], s[4:5]
	s_add_i32 s0, s15, s10
	s_ashr_i32 s0, s0, 3
	s_andn2_b32 s0, s0, 31
	s_and_b32 s1, s15, 0xc0
	s_add_i32 s0, s0, s8
	v_or_b32_e32 v152, s1, v150
	s_mul_hi_i32 s1, s0, 0x88000
	s_mul_i32 s0, s0, 0x88000
	v_lshlrev_b32_e32 v0, 3, v148
	s_add_u32 s0, s88, s0
	v_cndmask_b32_e64 v146, 0, 1, s[2:3]
	v_cndmask_b32_e32 v151, 1.0, v248, vcc
	v_or_b32_e32 v149, 0x1000, v152
	s_addc_u32 s1, s89, s1
	s_mov_b64 s[6:7], -1
	v_cmp_ne_u32_e64 s[4:5], 1, v146
	s_andn2_b64 vcc, exec, s[2:3]
	v_lshlrev_b32_e32 v146, 1, v0
	v_readlane_b32 s17, v252, 1
	v_readlane_b32 s20, v252, 4
	v_readlane_b32 s21, v252, 5
	v_readlane_b32 s22, v252, 6
	v_readlane_b32 s23, v252, 7
	v_readlane_b32 s24, v252, 8
	v_readlane_b32 s25, v252, 9
	v_readlane_b32 s26, v252, 10
	v_readlane_b32 s27, v252, 11
	v_readlane_b32 s28, v252, 12
	v_readlane_b32 s29, v252, 13
	v_readlane_b32 s30, v252, 14
	v_readlane_b32 s31, v252, 15
	s_cbranch_vccnz .LBB0_843
	v_mul_f32_e32 v0, v143, v143
	v_fmac_f32_e32 v0, v142, v142
	v_fmac_f32_e32 v0, v144, v144
	v_fmac_f32_e32 v0, v145, v145
	v_fmac_f32_e32 v0, v138, v138
	v_fmac_f32_e32 v0, v139, v139
	v_fmac_f32_e32 v0, v140, v140
	v_fmac_f32_e32 v0, v141, v141
	v_pk_mul_f32 v[156:157], v[134:135], v[134:135]
	v_pk_mul_f32 v[154:155], v[136:137], v[136:137]
	v_add_f32_e32 v0, v156, v0
	v_add_f32_e32 v0, v157, v0
	v_add_f32_e32 v0, v154, v0
	v_add_f32_e32 v0, v155, v0
	v_pk_mul_f32 v[156:157], v[130:131], v[130:131]
	v_add_f32_e32 v0, v156, v0
	v_pk_mul_f32 v[154:155], v[132:133], v[132:133]
	v_add_f32_e32 v0, v157, v0
	v_add_f32_e32 v0, v154, v0
	v_add_f32_e32 v0, v155, v0
	v_mov_b32_e32 v147, v0
	s_nop 1
	v_permlane16_swap_b32_e32 v0, v147
	s_mov_b64 s[6:7], 0
	s_waitcnt lgkmcnt(0)
	v_add_f32_e32 v0, v0, v147
	s_nop 1
	v_mov_b32_e32 v147, v0
	s_nop 1
	v_permlane32_swap_b32_e32 v0, v147
	s_waitcnt lgkmcnt(0)
	v_add_f32_e32 v0, v0, v147
	v_fmamk_f32 v0, v0, 0x3c800000, v210
	v_mul_f32_e32 v147, 0x4b800000, v0
	v_cmp_gt_f32_e32 vcc, s11, v0
	s_nop 1
	v_cndmask_b32_e32 v0, v0, v147, vcc
	v_rsq_f32_e32 v0, v0
	s_nop 0
	v_mul_f32_e32 v147, 0x45800000, v0
	v_cndmask_b32_e32 v0, v0, v147, vcc
	v_mul_f32_e32 v0, v151, v0
	v_pk_mul_f32 v[154:155], v[134:135], v[0:1] op_sel_hi:[1,0]
	v_pk_mul_f32 v[156:157], v[142:143], v[0:1] op_sel_hi:[1,0]
	s_waitcnt vmcnt(0)
	v_pk_mul_f32 v[154:155], v[94:95], v[154:155]
	v_pk_mul_f32 v[156:157], v[90:91], v[156:157]
	v_pk_mul_f32 v[160:161], v[144:145], v[0:1] op_sel_hi:[1,0]
	v_pk_fma_f32 v[158:159], v[156:157], 0, v[154:155] op_sel_hi:[1,0,1]
	v_pk_fma_f32 v[154:155], v[154:155], 0, v[156:157] op_sel_hi:[1,0,1] neg_lo:[1,0,0] neg_hi:[1,0,0]
	v_pk_mul_f32 v[156:157], v[136:137], v[0:1] op_sel_hi:[1,0]
	v_pk_mul_f32 v[160:161], v[92:93], v[160:161]
	v_pk_mul_f32 v[156:157], v[96:97], v[156:157]
	v_pk_mul_f32 v[164:165], v[138:139], v[0:1] op_sel_hi:[1,0]
	v_pk_fma_f32 v[162:163], v[160:161], 0, v[156:157] op_sel_hi:[1,0,1]
	v_pk_fma_f32 v[156:157], v[156:157], 0, v[160:161] op_sel_hi:[1,0,1] neg_lo:[1,0,0] neg_hi:[1,0,0]
	v_pk_mul_f32 v[160:161], v[130:131], v[0:1] op_sel_hi:[1,0]
	v_pk_mul_f32 v[164:165], v[82:83], v[164:165]
	v_pk_mul_f32 v[160:161], v[86:87], v[160:161]
	v_pk_mul_f32 v[168:169], v[140:141], v[0:1] op_sel_hi:[1,0]
	v_pk_fma_f32 v[166:167], v[164:165], 0, v[160:161] op_sel_hi:[1,0,1]
	v_pk_fma_f32 v[160:161], v[160:161], 0, v[164:165] op_sel_hi:[1,0,1] neg_lo:[1,0,0] neg_hi:[1,0,0]
	v_pk_mul_f32 v[164:165], v[132:133], v[0:1] op_sel_hi:[1,0]
	v_pk_mul_f32 v[168:169], v[84:85], v[168:169]
	v_pk_mul_f32 v[164:165], v[88:89], v[164:165]
	v_lshlrev_b32_e32 v0, 7, v149
	v_pk_fma_f32 v[170:171], v[168:169], 0, v[164:165] op_sel_hi:[1,0,1]
	v_pk_fma_f32 v[164:165], v[164:165], 0, v[168:169] op_sel_hi:[1,0,1] neg_lo:[1,0,0] neg_hi:[1,0,0]
	v_lshl_add_u64 v[168:169], s[0:1], 0, v[0:1]
	v_mov_b32_e32 v147, v1
	v_lshl_add_u64 v[168:169], v[168:169], 0, v[146:147]
	v_cvt_pk_bf16_f32 v154, v154, v155
	v_cvt_pk_bf16_f32 v155, v156, v157
	v_cvt_pk_bf16_f32 v156, v160, v161
	v_cvt_pk_bf16_f32 v157, v164, v165
	global_store_dwordx4 v[168:169], v[154:157], off
	s_nop 1
	v_cvt_pk_bf16_f32 v154, v158, v159
	v_cvt_pk_bf16_f32 v155, v162, v163
	v_cvt_pk_bf16_f32 v156, v166, v167
	v_cvt_pk_bf16_f32 v157, v170, v171
	global_store_dwordx4 v[168:169], v[154:157], off offset:64

; DI u16 f2bf(float a) { return (u16)(pack_bf16(a, 0.f) & 0xffffu); }
;   DI void operator()(const f32x4 (&acc)[2][2][4][2], const Unit& u, int wr, int wc, int fr, int fq) const {
;     ...
;         const int t = u.pm * BM + ai * HALF + wr * 64 + m * 16 + fr;
;         int b, pos;
;         if (rowbase == 0) { b = t >> 12; pos = t & 4095; } else { b = t >> 8; pos = 4096 + (t & 255); }
;         u16* base = qkv + (size_t)(b * 32 + chunk) * LTOT * 64;
;         if (isV) {
; #pragma unroll
;           for (int bj = 0; bj < 2; ++bj)
; #pragma unroll
;             for (int n = 0; n < 2; ++n)
; #pragma unroll
;               for (int e = 0; e < 4; ++e) {
;                 int d = 32 * bj + 8 * fq + 4 * n + e;
;                 base[(size_t)d * LTOT + pos] = f2bf(acc[ai][bj][m][n][e]);
;               }
;         } else {
;           float ss = 0.f;
; #pragma unroll
;           for (int bj = 0; bj < 2; ++bj)
; #pragma unroll
;             for (int n = 0; n < 2; ++n)
; #pragma unroll
;               for (int e = 0; e < 4; ++e) ss += acc[ai][bj][m][n][e] * acc[ai][bj][m][n][e];
;           ss += __shfl_xor(ss, 16);
;           ss += __shfl_xor(ss, 32);
;           const float rinv = rsqrtf(ss * (1.f / 64.f) + EPSV);
;           float o1[8], o2[8];
; #pragma unroll
;           for (int n = 0; n < 2; ++n) {
;             f32x4 cs0 = (f32x4){1.f, 0.f, 1.f, 0.f}, cs1 = cs0;
;             if (ropeT) { cs0 = csr[m & 1][n][0]; cs1 = csr[m & 1][n][1]; }
; #pragma unroll
;             for (int e = 0; e < 4; ++e) {
;               float x1 = acc[ai][0][m][n][e] * (rinv * qs) * g4[0][n][e];
;               float x2 = acc[ai][1][m][n][e] * (rinv * qs) * g4[1][n][e];
;               float c = (e < 2) ? cs0[2 * e] : cs1[2 * (e - 2)], s = (e < 2) ? cs0[2 * e + 1] : cs1[2 * (e - 2) + 1];
;               o1[n * 4 + e] = x1 * c - x2 * s;
;               o2[n * 4 + e] = x2 * c + x1 * s;
;             }
;           }
;           u16* dst = base + (size_t)pos * 64 + 8 * fq;
;           *(uint4*)(dst) = make_uint4(pack_bf16(o1[0], o1[1]), pack_bf16(o1[2], o1[3]), pack_bf16(o1[4], o1[5]), pack_bf16(o1[6], o1[7]));
;           *(uint4*)(dst + 32) = make_uint4(pack_bf16(o2[0], o2[1]), pack_bf16(o2[2], o2[3]), pack_bf16(o2[4], o2[5]), pack_bf16(o2[6], o2[7]));
.LBB0_845:
	v_or_b32_e32 v130, 0x1010, v152
	s_and_b64 vcc, exec, s[4:5]
	s_mov_b64 s[2:3], -1
	s_movk_i32 s28, 0x4000
	s_cbranch_vccnz .LBB0_851
	v_mul_f32_e32 v0, v127, v127
	v_fmac_f32_e32 v0, v126, v126
	v_fmac_f32_e32 v0, v128, v128
	v_fmac_f32_e32 v0, v129, v129
	v_fmac_f32_e32 v0, v122, v122
	v_fmac_f32_e32 v0, v123, v123
	v_fmac_f32_e32 v0, v124, v124
	v_fmac_f32_e32 v0, v125, v125
	v_pk_mul_f32 v[134:135], v[118:119], v[118:119]
	v_pk_mul_f32 v[132:133], v[120:121], v[120:121]
	v_add_f32_e32 v0, v134, v0
	v_add_f32_e32 v0, v135, v0
	v_add_f32_e32 v0, v132, v0
	v_add_f32_e32 v0, v133, v0
	v_pk_mul_f32 v[134:135], v[114:115], v[114:115]
	v_pk_mul_f32 v[132:133], v[116:117], v[116:117]
	v_add_f32_e32 v0, v134, v0
	v_add_f32_e32 v0, v135, v0
	v_add_f32_e32 v0, v132, v0
	v_add_f32_e32 v0, v133, v0
	v_mov_b32_e32 v147, v1
	v_mov_b32_e32 v131, v0
	s_nop 1
	v_permlane16_swap_b32_e32 v0, v131
	s_waitcnt lgkmcnt(0)
	v_add_f32_e32 v0, v0, v131
	s_nop 1
	v_mov_b32_e32 v131, v0
	s_nop 1
	v_permlane32_swap_b32_e32 v0, v131
	s_waitcnt lgkmcnt(0)
	v_add_f32_e32 v0, v0, v131
	v_fmamk_f32 v0, v0, 0x3c800000, v210
	v_mul_f32_e32 v131, 0x4b800000, v0
	v_cmp_gt_f32_e32 vcc, s11, v0
	s_nop 1
	v_cndmask_b32_e32 v0, v0, v131, vcc
	v_rsq_f32_e32 v0, v0
	s_nop 0
	v_mul_f32_e32 v131, 0x45800000, v0
	v_cndmask_b32_e32 v0, v0, v131, vcc
	v_mul_f32_e32 v0, v151, v0
	v_pk_mul_f32 v[132:133], v[118:119], v[0:1] op_sel_hi:[1,0]
	v_pk_mul_f32 v[134:135], v[126:127], v[0:1] op_sel_hi:[1,0]
	v_pk_mul_f32 v[132:133], v[94:95], v[132:133]
	v_pk_mul_f32 v[134:135], v[90:91], v[134:135]
	v_pk_mul_f32 v[138:139], v[128:129], v[0:1] op_sel_hi:[1,0]
	v_pk_fma_f32 v[136:137], v[134:135], 0, v[132:133] op_sel_hi:[1,0,1]
	v_pk_fma_f32 v[132:133], v[132:133], 0, v[134:135] op_sel_hi:[1,0,1] neg_lo:[1,0,0] neg_hi:[1,0,0]
	v_pk_mul_f32 v[134:135], v[120:121], v[0:1] op_sel_hi:[1,0]
	v_pk_mul_f32 v[138:139], v[92:93], v[138:139]
	v_pk_mul_f32 v[134:135], v[96:97], v[134:135]
	v_pk_mul_f32 v[142:143], v[122:123], v[0:1] op_sel_hi:[1,0]
	v_pk_fma_f32 v[140:141], v[138:139], 0, v[134:135] op_sel_hi:[1,0,1]
	v_pk_fma_f32 v[134:135], v[134:135], 0, v[138:139] op_sel_hi:[1,0,1] neg_lo:[1,0,0] neg_hi:[1,0,0]
	v_pk_mul_f32 v[138:139], v[114:115], v[0:1] op_sel_hi:[1,0]
	v_pk_mul_f32 v[142:143], v[82:83], v[142:143]
	v_pk_mul_f32 v[138:139], v[86:87], v[138:139]
	v_pk_mul_f32 v[154:155], v[124:125], v[0:1] op_sel_hi:[1,0]
	v_pk_fma_f32 v[144:145], v[142:143], 0, v[138:139] op_sel_hi:[1,0,1]
	v_pk_fma_f32 v[138:139], v[138:139], 0, v[142:143] op_sel_hi:[1,0,1] neg_lo:[1,0,0] neg_hi:[1,0,0]
	v_pk_mul_f32 v[142:143], v[116:117], v[0:1] op_sel_hi:[1,0]
	v_pk_mul_f32 v[154:155], v[84:85], v[154:155]
	v_pk_mul_f32 v[142:143], v[88:89], v[142:143]
	v_lshlrev_b32_e32 v0, 7, v130
	v_pk_fma_f32 v[156:157], v[154:155], 0, v[142:143] op_sel_hi:[1,0,1]
	v_pk_fma_f32 v[142:143], v[142:143], 0, v[154:155] op_sel_hi:[1,0,1] neg_lo:[1,0,0] neg_hi:[1,0,0]
	v_lshl_add_u64 v[154:155], s[0:1], 0, v[0:1]
	v_lshl_add_u64 v[154:155], v[154:155], 0, v[146:147]
	v_cvt_pk_bf16_f32 v132, v132, v133
	v_cvt_pk_bf16_f32 v133, v134, v135
	v_cvt_pk_bf16_f32 v134, v138, v139
	v_cvt_pk_bf16_f32 v135, v142, v143
	global_store_dwordx4 v[154:155], v[132:135], off
	s_nop 1
	v_cvt_pk_bf16_f32 v132, v136, v137
	v_cvt_pk_bf16_f32 v133, v140, v141
	v_cvt_pk_bf16_f32 v134, v144, v145
	v_cvt_pk_bf16_f32 v135, v156, v157
	global_store_dwordx4 v[154:155], v[132:135], off offset:64
	s_cbranch_execz .LBB0_852

; DI u16 f2bf(float a) { return (u16)(pack_bf16(a, 0.f) & 0xffffu); }
;   DI void operator()(const f32x4 (&acc)[2][2][4][2], const Unit& u, int wr, int wc, int fr, int fq) const {
;     ...
;         const int t = u.pm * BM + ai * HALF + wr * 64 + m * 16 + fr;
;         int b, pos;
;         if (rowbase == 0) { b = t >> 12; pos = t & 4095; } else { b = t >> 8; pos = 4096 + (t & 255); }
;         u16* base = qkv + (size_t)(b * 32 + chunk) * LTOT * 64;
;         if (isV) {
; #pragma unroll
;           for (int bj = 0; bj < 2; ++bj)
; #pragma unroll
;             for (int n = 0; n < 2; ++n)
; #pragma unroll
;               for (int e = 0; e < 4; ++e) {
;                 int d = 32 * bj + 8 * fq + 4 * n + e;
;                 base[(size_t)d * LTOT + pos] = f2bf(acc[ai][bj][m][n][e]);
;               }
;         } else {
;           float ss = 0.f;
; #pragma unroll
;           for (int bj = 0; bj < 2; ++bj)
; #pragma unroll
;             for (int n = 0; n < 2; ++n)
; #pragma unroll
;               for (int e = 0; e < 4; ++e) ss += acc[ai][bj][m][n][e] * acc[ai][bj][m][n][e];
;           ss += __shfl_xor(ss, 16);
;           ss += __shfl_xor(ss, 32);
;           const float rinv = rsqrtf(ss * (1.f / 64.f) + EPSV);
;           float o1[8], o2[8];
; #pragma unroll
;           for (int n = 0; n < 2; ++n) {
;             f32x4 cs0 = (f32x4){1.f, 0.f, 1.f, 0.f}, cs1 = cs0;
;             if (ropeT) { cs0 = csr[m & 1][n][0]; cs1 = csr[m & 1][n][1]; }
; #pragma unroll
;             for (int e = 0; e < 4; ++e) {
;               float x1 = acc[ai][0][m][n][e] * (rinv * qs) * g4[0][n][e];
;               float x2 = acc[ai][1][m][n][e] * (rinv * qs) * g4[1][n][e];
;               float c = (e < 2) ? cs0[2 * e] : cs1[2 * (e - 2)], s = (e < 2) ? cs0[2 * e + 1] : cs1[2 * (e - 2) + 1];
;               o1[n * 4 + e] = x1 * c - x2 * s;
;               o2[n * 4 + e] = x2 * c + x1 * s;
;             }
;           }
;           u16* dst = base + (size_t)pos * 64 + 8 * fq;
;           *(uint4*)(dst) = make_uint4(pack_bf16(o1[0], o1[1]), pack_bf16(o1[2], o1[3]), pack_bf16(o1[4], o1[5]), pack_bf16(o1[6], o1[7]));
;           *(uint4*)(dst + 32) = make_uint4(pack_bf16(o2[0], o2[1]), pack_bf16(o2[2], o2[3]), pack_bf16(o2[4], o2[5]), pack_bf16(o2[6], o2[7]));
.LBB0_848:
	v_mul_f32_e32 v0, v111, v111
	v_fmac_f32_e32 v0, v110, v110
	v_fmac_f32_e32 v0, v112, v112
	v_fmac_f32_e32 v0, v113, v113
	v_fmac_f32_e32 v0, v106, v106
	v_fmac_f32_e32 v0, v107, v107
	v_fmac_f32_e32 v0, v108, v108
	v_fmac_f32_e32 v0, v109, v109
	v_pk_mul_f32 v[118:119], v[102:103], v[102:103]
	v_pk_mul_f32 v[116:117], v[104:105], v[104:105]
	v_add_f32_e32 v0, v118, v0
	v_add_f32_e32 v0, v119, v0
	v_add_f32_e32 v0, v116, v0
	v_add_f32_e32 v0, v117, v0
	v_pk_mul_f32 v[118:119], v[98:99], v[98:99]
	v_pk_mul_f32 v[116:117], v[100:101], v[100:101]
	v_add_f32_e32 v0, v118, v0
	v_add_f32_e32 v0, v119, v0
	v_add_f32_e32 v0, v116, v0
	v_add_f32_e32 v0, v117, v0
	v_mov_b32_e32 v147, v1
	v_mov_b32_e32 v115, v0
	s_nop 1
	v_permlane16_swap_b32_e32 v0, v115
	s_waitcnt lgkmcnt(0)
	v_add_f32_e32 v0, v0, v115
	s_nop 1
	v_mov_b32_e32 v115, v0
	s_nop 1
	v_permlane32_swap_b32_e32 v0, v115
	s_waitcnt lgkmcnt(0)
	v_add_f32_e32 v0, v0, v115
	v_fmamk_f32 v0, v0, 0x3c800000, v210
	v_mul_f32_e32 v115, 0x4b800000, v0
	v_cmp_gt_f32_e32 vcc, s11, v0
	s_nop 1
	v_cndmask_b32_e32 v0, v0, v115, vcc
	v_rsq_f32_e32 v0, v0
	s_nop 0
	v_mul_f32_e32 v115, 0x45800000, v0
	v_cndmask_b32_e32 v0, v0, v115, vcc
	v_mul_f32_e32 v0, v151, v0
	v_pk_mul_f32 v[116:117], v[102:103], v[0:1] op_sel_hi:[1,0]
	v_pk_mul_f32 v[118:119], v[110:111], v[0:1] op_sel_hi:[1,0]
	v_pk_mul_f32 v[116:117], v[94:95], v[116:117]
	v_pk_mul_f32 v[118:119], v[90:91], v[118:119]
	v_pk_mul_f32 v[122:123], v[112:113], v[0:1] op_sel_hi:[1,0]
	v_pk_fma_f32 v[120:121], v[118:119], 0, v[116:117] op_sel_hi:[1,0,1]
	v_pk_fma_f32 v[116:117], v[116:117], 0, v[118:119] op_sel_hi:[1,0,1] neg_lo:[1,0,0] neg_hi:[1,0,0]
	v_pk_mul_f32 v[118:119], v[104:105], v[0:1] op_sel_hi:[1,0]
	v_pk_mul_f32 v[122:123], v[92:93], v[122:123]
	v_pk_mul_f32 v[118:119], v[96:97], v[118:119]
	v_pk_mul_f32 v[126:127], v[106:107], v[0:1] op_sel_hi:[1,0]
	v_pk_fma_f32 v[124:125], v[122:123], 0, v[118:119] op_sel_hi:[1,0,1]
	v_pk_fma_f32 v[118:119], v[118:119], 0, v[122:123] op_sel_hi:[1,0,1] neg_lo:[1,0,0] neg_hi:[1,0,0]
	v_pk_mul_f32 v[122:123], v[98:99], v[0:1] op_sel_hi:[1,0]
	v_pk_mul_f32 v[126:127], v[82:83], v[126:127]
	v_pk_mul_f32 v[122:123], v[86:87], v[122:123]
	v_pk_mul_f32 v[130:131], v[108:109], v[0:1] op_sel_hi:[1,0]
	v_pk_fma_f32 v[128:129], v[126:127], 0, v[122:123] op_sel_hi:[1,0,1]
	v_pk_fma_f32 v[122:123], v[122:123], 0, v[126:127] op_sel_hi:[1,0,1] neg_lo:[1,0,0] neg_hi:[1,0,0]
	v_pk_mul_f32 v[126:127], v[100:101], v[0:1] op_sel_hi:[1,0]
	v_pk_mul_f32 v[130:131], v[84:85], v[130:131]
	v_pk_mul_f32 v[126:127], v[88:89], v[126:127]
	v_lshlrev_b32_e32 v0, 7, v114
	v_pk_fma_f32 v[132:133], v[130:131], 0, v[126:127] op_sel_hi:[1,0,1]
	v_pk_fma_f32 v[126:127], v[126:127], 0, v[130:131] op_sel_hi:[1,0,1] neg_lo:[1,0,0] neg_hi:[1,0,0]
	v_lshl_add_u64 v[130:131], s[0:1], 0, v[0:1]
	v_lshl_add_u64 v[130:131], v[130:131], 0, v[146:147]
	v_cvt_pk_bf16_f32 v116, v116, v117
	v_cvt_pk_bf16_f32 v117, v118, v119
	v_cvt_pk_bf16_f32 v118, v122, v123
	v_cvt_pk_bf16_f32 v119, v126, v127
	global_store_dwordx4 v[130:131], v[116:119], off
	s_nop 1
	v_cvt_pk_bf16_f32 v116, v120, v121
	v_cvt_pk_bf16_f32 v117, v124, v125
	v_cvt_pk_bf16_f32 v118, v128, v129
	v_cvt_pk_bf16_f32 v119, v132, v133
	global_store_dwordx4 v[130:131], v[116:119], off offset:64
	s_cbranch_execz .LBB0_854

; DI u16 f2bf(float a) { return (u16)(pack_bf16(a, 0.f) & 0xffffu); }
;   DI void operator()(const f32x4 (&acc)[2][2][4][2], const Unit& u, int wr, int wc, int fr, int fq) const {
;     ...
;         const int t = u.pm * BM + ai * HALF + wr * 64 + m * 16 + fr;
;         int b, pos;
;         if (rowbase == 0) { b = t >> 12; pos = t & 4095; } else { b = t >> 8; pos = 4096 + (t & 255); }
;         u16* base = qkv + (size_t)(b * 32 + chunk) * LTOT * 64;
;         if (isV) {
; #pragma unroll
;           for (int bj = 0; bj < 2; ++bj)
; #pragma unroll
;             for (int n = 0; n < 2; ++n)
; #pragma unroll
;               for (int e = 0; e < 4; ++e) {
;                 int d = 32 * bj + 8 * fq + 4 * n + e;
;                 base[(size_t)d * LTOT + pos] = f2bf(acc[ai][bj][m][n][e]);
;               }
;         } else {
;           float ss = 0.f;
; #pragma unroll
;           for (int bj = 0; bj < 2; ++bj)
; #pragma unroll
;             for (int n = 0; n < 2; ++n)
; #pragma unroll
;               for (int e = 0; e < 4; ++e) ss += acc[ai][bj][m][n][e] * acc[ai][bj][m][n][e];
;           ss += __shfl_xor(ss, 16);
;           ss += __shfl_xor(ss, 32);
;           const float rinv = rsqrtf(ss * (1.f / 64.f) + EPSV);
;           float o1[8], o2[8];
; #pragma unroll
;           for (int n = 0; n < 2; ++n) {
;             f32x4 cs0 = (f32x4){1.f, 0.f, 1.f, 0.f}, cs1 = cs0;
;             if (ropeT) { cs0 = csr[m & 1][n][0]; cs1 = csr[m & 1][n][1]; }
; #pragma unroll
;             for (int e = 0; e < 4; ++e) {
;               float x1 = acc[ai][0][m][n][e] * (rinv * qs) * g4[0][n][e];
;               float x2 = acc[ai][1][m][n][e] * (rinv * qs) * g4[1][n][e];
;               float c = (e < 2) ? cs0[2 * e] : cs1[2 * (e - 2)], s = (e < 2) ? cs0[2 * e + 1] : cs1[2 * (e - 2) + 1];
;               o1[n * 4 + e] = x1 * c - x2 * s;
;               o2[n * 4 + e] = x2 * c + x1 * s;
;             }
;           }
;           u16* dst = base + (size_t)pos * 64 + 8 * fq;
;           *(uint4*)(dst) = make_uint4(pack_bf16(o1[0], o1[1]), pack_bf16(o1[2], o1[3]), pack_bf16(o1[4], o1[5]), pack_bf16(o1[6], o1[7]));
;           *(uint4*)(dst + 32) = make_uint4(pack_bf16(o2[0], o2[1]), pack_bf16(o2[2], o2[3]), pack_bf16(o2[4], o2[5]), pack_bf16(o2[6], o2[7]));
.LBB0_850:
	v_mul_f32_e32 v0, v79, v79
	v_fmac_f32_e32 v0, v78, v78
	v_fmac_f32_e32 v0, v80, v80
	v_fmac_f32_e32 v0, v81, v81
	v_fmac_f32_e32 v0, v74, v74
	v_fmac_f32_e32 v0, v75, v75
	v_fmac_f32_e32 v0, v76, v76
	v_fmac_f32_e32 v0, v77, v77
	v_pk_mul_f32 v[102:103], v[70:71], v[70:71]
	v_pk_mul_f32 v[100:101], v[72:73], v[72:73]
	v_add_f32_e32 v0, v102, v0
	v_add_f32_e32 v0, v103, v0
	v_add_f32_e32 v0, v100, v0
	v_add_f32_e32 v0, v101, v0
	v_pk_mul_f32 v[102:103], v[66:67], v[66:67]
	v_pk_mul_f32 v[100:101], v[68:69], v[68:69]
	v_add_f32_e32 v0, v102, v0
	v_add_f32_e32 v0, v103, v0
	v_add_f32_e32 v0, v100, v0
	v_add_f32_e32 v0, v101, v0
	v_mov_b32_e32 v147, v1
	v_mov_b32_e32 v99, v0
	s_nop 1
	v_permlane16_swap_b32_e32 v0, v99
	s_waitcnt lgkmcnt(0)
	v_add_f32_e32 v0, v0, v99
	s_nop 1
	v_mov_b32_e32 v99, v0
	s_nop 1
	v_permlane32_swap_b32_e32 v0, v99
	s_waitcnt lgkmcnt(0)
	v_add_f32_e32 v0, v0, v99
	v_fmamk_f32 v0, v0, 0x3c800000, v210
	v_mul_f32_e32 v99, 0x4b800000, v0
	v_cmp_gt_f32_e32 vcc, s11, v0
	s_nop 1
	v_cndmask_b32_e32 v0, v0, v99, vcc
	v_rsq_f32_e32 v0, v0
	s_nop 0
	v_mul_f32_e32 v99, 0x45800000, v0
	v_cndmask_b32_e32 v0, v0, v99, vcc
	v_mul_f32_e32 v0, v151, v0
	v_pk_mul_f32 v[100:101], v[70:71], v[0:1] op_sel_hi:[1,0]
	v_pk_mul_f32 v[102:103], v[78:79], v[0:1] op_sel_hi:[1,0]
	v_pk_mul_f32 v[100:101], v[94:95], v[100:101]
	v_pk_mul_f32 v[102:103], v[90:91], v[102:103]
	v_pk_mul_f32 v[106:107], v[80:81], v[0:1] op_sel_hi:[1,0]
	v_pk_fma_f32 v[104:105], v[102:103], 0, v[100:101] op_sel_hi:[1,0,1]
	v_pk_fma_f32 v[100:101], v[100:101], 0, v[102:103] op_sel_hi:[1,0,1] neg_lo:[1,0,0] neg_hi:[1,0,0]
	v_pk_mul_f32 v[102:103], v[72:73], v[0:1] op_sel_hi:[1,0]
	v_pk_mul_f32 v[106:107], v[92:93], v[106:107]
	v_pk_mul_f32 v[102:103], v[96:97], v[102:103]
	v_pk_mul_f32 v[110:111], v[74:75], v[0:1] op_sel_hi:[1,0]
	v_pk_fma_f32 v[108:109], v[106:107], 0, v[102:103] op_sel_hi:[1,0,1]
	v_pk_fma_f32 v[102:103], v[102:103], 0, v[106:107] op_sel_hi:[1,0,1] neg_lo:[1,0,0] neg_hi:[1,0,0]
	v_pk_mul_f32 v[106:107], v[66:67], v[0:1] op_sel_hi:[1,0]
	v_pk_mul_f32 v[110:111], v[82:83], v[110:111]
	v_pk_mul_f32 v[106:107], v[86:87], v[106:107]
	v_pk_mul_f32 v[114:115], v[76:77], v[0:1] op_sel_hi:[1,0]
	v_pk_fma_f32 v[112:113], v[110:111], 0, v[106:107] op_sel_hi:[1,0,1]
	v_pk_fma_f32 v[106:107], v[106:107], 0, v[110:111] op_sel_hi:[1,0,1] neg_lo:[1,0,0] neg_hi:[1,0,0]
	v_pk_mul_f32 v[110:111], v[68:69], v[0:1] op_sel_hi:[1,0]
	v_pk_mul_f32 v[114:115], v[84:85], v[114:115]
	v_pk_mul_f32 v[110:111], v[88:89], v[110:111]
	v_lshlrev_b32_e32 v0, 7, v98
	v_pk_fma_f32 v[116:117], v[114:115], 0, v[110:111] op_sel_hi:[1,0,1]
	v_pk_fma_f32 v[110:111], v[110:111], 0, v[114:115] op_sel_hi:[1,0,1] neg_lo:[1,0,0] neg_hi:[1,0,0]
	v_lshl_add_u64 v[114:115], s[0:1], 0, v[0:1]
	v_lshl_add_u64 v[114:115], v[114:115], 0, v[146:147]
	v_cvt_pk_bf16_f32 v100, v100, v101
	v_cvt_pk_bf16_f32 v101, v102, v103
	v_cvt_pk_bf16_f32 v102, v106, v107
	v_cvt_pk_bf16_f32 v103, v110, v111
	global_store_dwordx4 v[114:115], v[100:103], off
	s_nop 1
	v_cvt_pk_bf16_f32 v100, v104, v105
	v_cvt_pk_bf16_f32 v101, v108, v109
	v_cvt_pk_bf16_f32 v102, v112, v113
	v_cvt_pk_bf16_f32 v103, v116, v117
	global_store_dwordx4 v[114:115], v[100:103], off offset:64
	s_cbranch_execz .LBB0_856
	s_branch .LBB0_857

; DI u16 f2bf(float a) { return (u16)(pack_bf16(a, 0.f) & 0xffffu); }
;   DI void operator()(const f32x4 (&acc)[2][2][4][2], const Unit& u, int wr, int wc, int fr, int fq) const {
;     ...
;         const int t = u.pm * BM + ai * HALF + wr * 64 + m * 16 + fr;
;         int b, pos;
;         if (rowbase == 0) { b = t >> 12; pos = t & 4095; } else { b = t >> 8; pos = 4096 + (t & 255); }
;         u16* base = qkv + (size_t)(b * 32 + chunk) * LTOT * 64;
;         if (isV) {
; #pragma unroll
;           for (int bj = 0; bj < 2; ++bj)
; #pragma unroll
;             for (int n = 0; n < 2; ++n)
; #pragma unroll
;               for (int e = 0; e < 4; ++e) {
;                 int d = 32 * bj + 8 * fq + 4 * n + e;
;                 base[(size_t)d * LTOT + pos] = f2bf(acc[ai][bj][m][n][e]);
;               }
;         } else {
;           float ss = 0.f;
; #pragma unroll
;           for (int bj = 0; bj < 2; ++bj)
; #pragma unroll
;             for (int n = 0; n < 2; ++n)
; #pragma unroll
;               for (int e = 0; e < 4; ++e) ss += acc[ai][bj][m][n][e] * acc[ai][bj][m][n][e];
;           ss += __shfl_xor(ss, 16);
;           ss += __shfl_xor(ss, 32);
;           const float rinv = rsqrtf(ss * (1.f / 64.f) + EPSV);
;           float o1[8], o2[8];
; #pragma unroll
;           for (int n = 0; n < 2; ++n) {
;             f32x4 cs0 = (f32x4){1.f, 0.f, 1.f, 0.f}, cs1 = cs0;
;             if (ropeT) { cs0 = csr[m & 1][n][0]; cs1 = csr[m & 1][n][1]; }
; #pragma unroll
;             for (int e = 0; e < 4; ++e) {
;               float x1 = acc[ai][0][m][n][e] * (rinv * qs) * g4[0][n][e];
;               float x2 = acc[ai][1][m][n][e] * (rinv * qs) * g4[1][n][e];
;               float c = (e < 2) ? cs0[2 * e] : cs1[2 * (e - 2)], s = (e < 2) ? cs0[2 * e + 1] : cs1[2 * (e - 2) + 1];
;               o1[n * 4 + e] = x1 * c - x2 * s;
;               o2[n * 4 + e] = x2 * c + x1 * s;
;             }
;           }
;           u16* dst = base + (size_t)pos * 64 + 8 * fq;
;           *(uint4*)(dst) = make_uint4(pack_bf16(o1[0], o1[1]), pack_bf16(o1[2], o1[3]), pack_bf16(o1[4], o1[5]), pack_bf16(o1[6], o1[7]));
;           *(uint4*)(dst + 32) = make_uint4(pack_bf16(o2[0], o2[1]), pack_bf16(o2[2], o2[3]), pack_bf16(o2[4], o2[5]), pack_bf16(o2[6], o2[7]));
.LBB0_857:
	s_add_i32 s0, s15, 0x80
	s_add_i32 s1, s0, s10
	s_and_b32 s0, s0, 0xc0
	v_or_b32_e32 v0, s0, v150
	s_ashr_i32 s0, s1, 3
	s_andn2_b32 s0, s0, 31
	s_add_i32 s0, s0, s8
	s_mul_hi_i32 s1, s0, 0x88000
	s_mul_i32 s0, s0, 0x88000
	s_add_u32 s0, s88, s0
	v_or_b32_e32 v66, 0x1000, v0
	s_addc_u32 s1, s89, s1
	s_and_b64 vcc, exec, s[4:5]
	s_mov_b64 s[2:3], -1
	s_cbranch_vccnz .LBB0_859
	v_mul_f32_e32 v0, v63, v63
	v_fmac_f32_e32 v0, v62, v62
	v_fmac_f32_e32 v0, v64, v64
	v_fmac_f32_e32 v0, v65, v65
	v_fmac_f32_e32 v0, v58, v58
	v_fmac_f32_e32 v0, v59, v59
	v_fmac_f32_e32 v0, v60, v60
	v_fmac_f32_e32 v0, v61, v61
	v_pk_mul_f32 v[70:71], v[54:55], v[54:55]
	v_pk_mul_f32 v[68:69], v[56:57], v[56:57]
	v_add_f32_e32 v0, v70, v0
	v_add_f32_e32 v0, v71, v0
	v_add_f32_e32 v0, v68, v0
	v_add_f32_e32 v0, v69, v0
	v_pk_mul_f32 v[70:71], v[50:51], v[50:51]
	v_pk_mul_f32 v[68:69], v[52:53], v[52:53]
	v_add_f32_e32 v0, v70, v0
	v_add_f32_e32 v0, v71, v0
	v_add_f32_e32 v0, v68, v0
	v_add_f32_e32 v0, v69, v0
	v_mov_b32_e32 v147, v1
	v_mov_b32_e32 v67, v0
	s_nop 1
	v_permlane16_swap_b32_e32 v0, v67
	s_mov_b64 s[2:3], 0
	s_waitcnt lgkmcnt(0)
	v_add_f32_e32 v0, v0, v67
	s_nop 1
	v_mov_b32_e32 v67, v0
	s_nop 1
	v_permlane32_swap_b32_e32 v0, v67
	s_waitcnt lgkmcnt(0)
	v_add_f32_e32 v0, v0, v67
	v_fmamk_f32 v0, v0, 0x3c800000, v210
	v_mul_f32_e32 v67, 0x4b800000, v0
	v_cmp_gt_f32_e32 vcc, s11, v0
	s_nop 1
	v_cndmask_b32_e32 v0, v0, v67, vcc
	v_rsq_f32_e32 v0, v0
	s_nop 0
	v_mul_f32_e32 v67, 0x45800000, v0
	v_cndmask_b32_e32 v0, v0, v67, vcc
	v_mul_f32_e32 v0, v151, v0
	v_pk_mul_f32 v[68:69], v[54:55], v[0:1] op_sel_hi:[1,0]
	v_pk_mul_f32 v[70:71], v[62:63], v[0:1] op_sel_hi:[1,0]
	v_pk_mul_f32 v[68:69], v[94:95], v[68:69]
	v_pk_mul_f32 v[70:71], v[90:91], v[70:71]
	v_pk_mul_f32 v[74:75], v[64:65], v[0:1] op_sel_hi:[1,0]
	v_pk_fma_f32 v[72:73], v[70:71], 0, v[68:69] op_sel_hi:[1,0,1]
	v_pk_fma_f32 v[68:69], v[68:69], 0, v[70:71] op_sel_hi:[1,0,1] neg_lo:[1,0,0] neg_hi:[1,0,0]
	v_pk_mul_f32 v[70:71], v[56:57], v[0:1] op_sel_hi:[1,0]
	v_pk_mul_f32 v[74:75], v[92:93], v[74:75]
	v_pk_mul_f32 v[70:71], v[96:97], v[70:71]
	v_pk_mul_f32 v[78:79], v[58:59], v[0:1] op_sel_hi:[1,0]
	v_pk_fma_f32 v[76:77], v[74:75], 0, v[70:71] op_sel_hi:[1,0,1]
	v_pk_fma_f32 v[70:71], v[70:71], 0, v[74:75] op_sel_hi:[1,0,1] neg_lo:[1,0,0] neg_hi:[1,0,0]
	v_pk_mul_f32 v[74:75], v[50:51], v[0:1] op_sel_hi:[1,0]
	v_pk_mul_f32 v[78:79], v[82:83], v[78:79]
	v_pk_mul_f32 v[74:75], v[86:87], v[74:75]
	v_pk_mul_f32 v[98:99], v[60:61], v[0:1] op_sel_hi:[1,0]
	v_pk_fma_f32 v[80:81], v[78:79], 0, v[74:75] op_sel_hi:[1,0,1]
	v_pk_fma_f32 v[74:75], v[74:75], 0, v[78:79] op_sel_hi:[1,0,1] neg_lo:[1,0,0] neg_hi:[1,0,0]
	v_pk_mul_f32 v[78:79], v[52:53], v[0:1] op_sel_hi:[1,0]
	v_pk_mul_f32 v[98:99], v[84:85], v[98:99]
	v_pk_mul_f32 v[78:79], v[88:89], v[78:79]
	v_lshlrev_b32_e32 v0, 7, v66
	v_pk_fma_f32 v[100:101], v[98:99], 0, v[78:79] op_sel_hi:[1,0,1]
	v_pk_fma_f32 v[78:79], v[78:79], 0, v[98:99] op_sel_hi:[1,0,1] neg_lo:[1,0,0] neg_hi:[1,0,0]
	v_lshl_add_u64 v[98:99], s[0:1], 0, v[0:1]
	v_lshl_add_u64 v[98:99], v[98:99], 0, v[146:147]
	v_cvt_pk_bf16_f32 v68, v68, v69
	v_cvt_pk_bf16_f32 v69, v70, v71
	v_cvt_pk_bf16_f32 v70, v74, v75
	v_cvt_pk_bf16_f32 v71, v78, v79
	global_store_dwordx4 v[98:99], v[68:71], off
	s_nop 1
	v_cvt_pk_bf16_f32 v68, v72, v73
	v_cvt_pk_bf16_f32 v69, v76, v77
	v_cvt_pk_bf16_f32 v70, v80, v81
	v_cvt_pk_bf16_f32 v71, v100, v101
	global_store_dwordx4 v[98:99], v[68:71], off offset:64

; DI u16 f2bf(float a) { return (u16)(pack_bf16(a, 0.f) & 0xffffu); }
;   DI void operator()(const f32x4 (&acc)[2][2][4][2], const Unit& u, int wr, int wc, int fr, int fq) const {
;     ...
;         const int t = u.pm * BM + ai * HALF + wr * 64 + m * 16 + fr;
;         int b, pos;
;         if (rowbase == 0) { b = t >> 12; pos = t & 4095; } else { b = t >> 8; pos = 4096 + (t & 255); }
;         u16* base = qkv + (size_t)(b * 32 + chunk) * LTOT * 64;
;         if (isV) {
; #pragma unroll
;           for (int bj = 0; bj < 2; ++bj)
; #pragma unroll
;             for (int n = 0; n < 2; ++n)
; #pragma unroll
;               for (int e = 0; e < 4; ++e) {
;                 int d = 32 * bj + 8 * fq + 4 * n + e;
;                 base[(size_t)d * LTOT + pos] = f2bf(acc[ai][bj][m][n][e]);
;               }
;         } else {
;           float ss = 0.f;
; #pragma unroll
;           for (int bj = 0; bj < 2; ++bj)
; #pragma unroll
;             for (int n = 0; n < 2; ++n)
; #pragma unroll
;               for (int e = 0; e < 4; ++e) ss += acc[ai][bj][m][n][e] * acc[ai][bj][m][n][e];
;           ss += __shfl_xor(ss, 16);
;           ss += __shfl_xor(ss, 32);
;           const float rinv = rsqrtf(ss * (1.f / 64.f) + EPSV);
;           float o1[8], o2[8];
; #pragma unroll
;           for (int n = 0; n < 2; ++n) {
;             f32x4 cs0 = (f32x4){1.f, 0.f, 1.f, 0.f}, cs1 = cs0;
;             if (ropeT) { cs0 = csr[m & 1][n][0]; cs1 = csr[m & 1][n][1]; }
; #pragma unroll
;             for (int e = 0; e < 4; ++e) {
;               float x1 = acc[ai][0][m][n][e] * (rinv * qs) * g4[0][n][e];
;               float x2 = acc[ai][1][m][n][e] * (rinv * qs) * g4[1][n][e];
;               float c = (e < 2) ? cs0[2 * e] : cs1[2 * (e - 2)], s = (e < 2) ? cs0[2 * e + 1] : cs1[2 * (e - 2) + 1];
;               o1[n * 4 + e] = x1 * c - x2 * s;
;               o2[n * 4 + e] = x2 * c + x1 * s;
;             }
;           }
;           u16* dst = base + (size_t)pos * 64 + 8 * fq;
;           *(uint4*)(dst) = make_uint4(pack_bf16(o1[0], o1[1]), pack_bf16(o1[2], o1[3]), pack_bf16(o1[4], o1[5]), pack_bf16(o1[6], o1[7]));
;           *(uint4*)(dst + 32) = make_uint4(pack_bf16(o2[0], o2[1]), pack_bf16(o2[2], o2[3]), pack_bf16(o2[4], o2[5]), pack_bf16(o2[6], o2[7]));
.LBB0_861:
	s_add_i32 s0, s15, 0x90
	s_add_i32 s1, s0, s10
	s_and_b32 s0, s0, 0xd0
	v_or_b32_e32 v0, s0, v150
	s_ashr_i32 s0, s1, 3
	s_andn2_b32 s0, s0, 31
	s_add_i32 s0, s0, s8
	s_mul_hi_i32 s1, s0, 0x88000
	s_mul_i32 s0, s0, 0x88000
	s_add_u32 s0, s88, s0
	v_or_b32_e32 v50, 0x1000, v0
	s_addc_u32 s1, s89, s1
	s_and_b64 vcc, exec, s[4:5]
	s_mov_b64 s[2:3], -1
	s_cbranch_vccnz .LBB0_863
	v_mul_f32_e32 v0, v47, v47
	v_fmac_f32_e32 v0, v46, v46
	v_fmac_f32_e32 v0, v48, v48
	v_fmac_f32_e32 v0, v49, v49
	v_fmac_f32_e32 v0, v42, v42
	v_fmac_f32_e32 v0, v43, v43
	v_fmac_f32_e32 v0, v44, v44
	v_fmac_f32_e32 v0, v45, v45
	v_pk_mul_f32 v[54:55], v[38:39], v[38:39]
	v_pk_mul_f32 v[52:53], v[40:41], v[40:41]
	v_add_f32_e32 v0, v54, v0
	v_add_f32_e32 v0, v55, v0
	v_add_f32_e32 v0, v52, v0
	v_add_f32_e32 v0, v53, v0
	v_pk_mul_f32 v[54:55], v[34:35], v[34:35]
	v_pk_mul_f32 v[52:53], v[36:37], v[36:37]
	v_add_f32_e32 v0, v54, v0
	v_add_f32_e32 v0, v55, v0
	v_add_f32_e32 v0, v52, v0
	v_add_f32_e32 v0, v53, v0
	v_mov_b32_e32 v147, v1
	v_mov_b32_e32 v51, v0
	s_nop 1
	v_permlane16_swap_b32_e32 v0, v51
	s_mov_b64 s[2:3], 0
	s_waitcnt lgkmcnt(0)
	v_add_f32_e32 v0, v0, v51
	s_nop 1
	v_mov_b32_e32 v51, v0
	s_nop 1
	v_permlane32_swap_b32_e32 v0, v51
	s_waitcnt lgkmcnt(0)
	v_add_f32_e32 v0, v0, v51
	v_fmamk_f32 v0, v0, 0x3c800000, v210
	v_mul_f32_e32 v51, 0x4b800000, v0
	v_cmp_gt_f32_e32 vcc, s11, v0
	s_nop 1
	v_cndmask_b32_e32 v0, v0, v51, vcc
	v_rsq_f32_e32 v0, v0
	s_nop 0
	v_mul_f32_e32 v51, 0x45800000, v0
	v_cndmask_b32_e32 v0, v0, v51, vcc
	v_mul_f32_e32 v0, v151, v0
	v_pk_mul_f32 v[52:53], v[38:39], v[0:1] op_sel_hi:[1,0]
	v_pk_mul_f32 v[54:55], v[46:47], v[0:1] op_sel_hi:[1,0]
	v_pk_mul_f32 v[52:53], v[94:95], v[52:53]
	v_pk_mul_f32 v[54:55], v[90:91], v[54:55]
	v_pk_mul_f32 v[58:59], v[48:49], v[0:1] op_sel_hi:[1,0]
	v_pk_fma_f32 v[56:57], v[54:55], 0, v[52:53] op_sel_hi:[1,0,1]
	v_pk_fma_f32 v[52:53], v[52:53], 0, v[54:55] op_sel_hi:[1,0,1] neg_lo:[1,0,0] neg_hi:[1,0,0]
	v_pk_mul_f32 v[54:55], v[40:41], v[0:1] op_sel_hi:[1,0]
	v_pk_mul_f32 v[58:59], v[92:93], v[58:59]
	v_pk_mul_f32 v[54:55], v[96:97], v[54:55]
	v_pk_mul_f32 v[62:63], v[42:43], v[0:1] op_sel_hi:[1,0]
	v_pk_fma_f32 v[60:61], v[58:59], 0, v[54:55] op_sel_hi:[1,0,1]
	v_pk_fma_f32 v[54:55], v[54:55], 0, v[58:59] op_sel_hi:[1,0,1] neg_lo:[1,0,0] neg_hi:[1,0,0]
	v_pk_mul_f32 v[58:59], v[34:35], v[0:1] op_sel_hi:[1,0]
	v_pk_mul_f32 v[62:63], v[82:83], v[62:63]
	v_pk_mul_f32 v[58:59], v[86:87], v[58:59]
	v_pk_mul_f32 v[66:67], v[44:45], v[0:1] op_sel_hi:[1,0]
	v_pk_fma_f32 v[64:65], v[62:63], 0, v[58:59] op_sel_hi:[1,0,1]
	v_pk_fma_f32 v[58:59], v[58:59], 0, v[62:63] op_sel_hi:[1,0,1] neg_lo:[1,0,0] neg_hi:[1,0,0]
	v_pk_mul_f32 v[62:63], v[36:37], v[0:1] op_sel_hi:[1,0]
	v_pk_mul_f32 v[66:67], v[84:85], v[66:67]
	v_pk_mul_f32 v[62:63], v[88:89], v[62:63]
	v_lshlrev_b32_e32 v0, 7, v50
	v_pk_fma_f32 v[68:69], v[66:67], 0, v[62:63] op_sel_hi:[1,0,1]
	v_pk_fma_f32 v[62:63], v[62:63], 0, v[66:67] op_sel_hi:[1,0,1] neg_lo:[1,0,0] neg_hi:[1,0,0]
	v_lshl_add_u64 v[66:67], s[0:1], 0, v[0:1]
	v_lshl_add_u64 v[66:67], v[66:67], 0, v[146:147]
	v_cvt_pk_bf16_f32 v52, v52, v53
	v_cvt_pk_bf16_f32 v53, v54, v55
	v_cvt_pk_bf16_f32 v54, v58, v59
	v_cvt_pk_bf16_f32 v55, v62, v63
	global_store_dwordx4 v[66:67], v[52:55], off
	s_nop 1
	v_cvt_pk_bf16_f32 v52, v56, v57
	v_cvt_pk_bf16_f32 v53, v60, v61
	v_cvt_pk_bf16_f32 v54, v64, v65
	v_cvt_pk_bf16_f32 v55, v68, v69
	global_store_dwordx4 v[66:67], v[52:55], off offset:64

; DI u16 f2bf(float a) { return (u16)(pack_bf16(a, 0.f) & 0xffffu); }
;   DI void operator()(const f32x4 (&acc)[2][2][4][2], const Unit& u, int wr, int wc, int fr, int fq) const {
;     ...
;         const int t = u.pm * BM + ai * HALF + wr * 64 + m * 16 + fr;
;         int b, pos;
;         if (rowbase == 0) { b = t >> 12; pos = t & 4095; } else { b = t >> 8; pos = 4096 + (t & 255); }
;         u16* base = qkv + (size_t)(b * 32 + chunk) * LTOT * 64;
;         if (isV) {
; #pragma unroll
;           for (int bj = 0; bj < 2; ++bj)
; #pragma unroll
;             for (int n = 0; n < 2; ++n)
; #pragma unroll
;               for (int e = 0; e < 4; ++e) {
;                 int d = 32 * bj + 8 * fq + 4 * n + e;
;                 base[(size_t)d * LTOT + pos] = f2bf(acc[ai][bj][m][n][e]);
;               }
;         } else {
;           float ss = 0.f;
; #pragma unroll
;           for (int bj = 0; bj < 2; ++bj)
; #pragma unroll
;             for (int n = 0; n < 2; ++n)
; #pragma unroll
;               for (int e = 0; e < 4; ++e) ss += acc[ai][bj][m][n][e] * acc[ai][bj][m][n][e];
;           ss += __shfl_xor(ss, 16);
;           ss += __shfl_xor(ss, 32);
;           const float rinv = rsqrtf(ss * (1.f / 64.f) + EPSV);
;           float o1[8], o2[8];
; #pragma unroll
;           for (int n = 0; n < 2; ++n) {
;             f32x4 cs0 = (f32x4){1.f, 0.f, 1.f, 0.f}, cs1 = cs0;
;             if (ropeT) { cs0 = csr[m & 1][n][0]; cs1 = csr[m & 1][n][1]; }
; #pragma unroll
;             for (int e = 0; e < 4; ++e) {
;               float x1 = acc[ai][0][m][n][e] * (rinv * qs) * g4[0][n][e];
;               float x2 = acc[ai][1][m][n][e] * (rinv * qs) * g4[1][n][e];
;               float c = (e < 2) ? cs0[2 * e] : cs1[2 * (e - 2)], s = (e < 2) ? cs0[2 * e + 1] : cs1[2 * (e - 2) + 1];
;               o1[n * 4 + e] = x1 * c - x2 * s;
;               o2[n * 4 + e] = x2 * c + x1 * s;
;             }
;           }
;           u16* dst = base + (size_t)pos * 64 + 8 * fq;
;           *(uint4*)(dst) = make_uint4(pack_bf16(o1[0], o1[1]), pack_bf16(o1[2], o1[3]), pack_bf16(o1[4], o1[5]), pack_bf16(o1[6], o1[7]));
;           *(uint4*)(dst + 32) = make_uint4(pack_bf16(o2[0], o2[1]), pack_bf16(o2[2], o2[3]), pack_bf16(o2[4], o2[5]), pack_bf16(o2[6], o2[7]));
.LBB0_865:
	s_add_i32 s0, s15, 0xa0
	s_add_i32 s1, s0, s10
	s_and_b32 s0, s0, 0xe0
	v_or_b32_e32 v0, s0, v150
	s_ashr_i32 s0, s1, 3
	s_andn2_b32 s0, s0, 31
	s_add_i32 s0, s0, s8
	s_mul_hi_i32 s1, s0, 0x88000
	s_mul_i32 s0, s0, 0x88000
	s_add_u32 s0, s88, s0
	v_or_b32_e32 v34, 0x1000, v0
	s_addc_u32 s1, s89, s1
	s_and_b64 vcc, exec, s[4:5]
	s_mov_b64 s[2:3], -1
	s_cbranch_vccnz .LBB0_867
	v_mul_f32_e32 v0, v31, v31
	v_fmac_f32_e32 v0, v30, v30
	v_fmac_f32_e32 v0, v32, v32
	v_fmac_f32_e32 v0, v33, v33
	v_fmac_f32_e32 v0, v26, v26
	v_fmac_f32_e32 v0, v27, v27
	v_fmac_f32_e32 v0, v28, v28
	v_fmac_f32_e32 v0, v29, v29
	v_pk_mul_f32 v[38:39], v[22:23], v[22:23]
	v_pk_mul_f32 v[36:37], v[24:25], v[24:25]
	v_add_f32_e32 v0, v38, v0
	v_add_f32_e32 v0, v39, v0
	v_add_f32_e32 v0, v36, v0
	v_add_f32_e32 v0, v37, v0
	v_pk_mul_f32 v[38:39], v[18:19], v[18:19]
	v_pk_mul_f32 v[36:37], v[20:21], v[20:21]
	v_add_f32_e32 v0, v38, v0
	v_add_f32_e32 v0, v39, v0
	v_add_f32_e32 v0, v36, v0
	v_add_f32_e32 v0, v37, v0
	v_mov_b32_e32 v147, v1
	v_mov_b32_e32 v35, v0
	s_nop 1
	v_permlane16_swap_b32_e32 v0, v35
	s_mov_b64 s[2:3], 0
	s_waitcnt lgkmcnt(0)
	v_add_f32_e32 v0, v0, v35
	s_nop 1
	v_mov_b32_e32 v35, v0
	s_nop 1
	v_permlane32_swap_b32_e32 v0, v35
	s_waitcnt lgkmcnt(0)
	v_add_f32_e32 v0, v0, v35
	v_fmamk_f32 v0, v0, 0x3c800000, v210
	v_mul_f32_e32 v35, 0x4b800000, v0
	v_cmp_gt_f32_e32 vcc, s11, v0
	s_nop 1
	v_cndmask_b32_e32 v0, v0, v35, vcc
	v_rsq_f32_e32 v0, v0
	s_nop 0
	v_mul_f32_e32 v35, 0x45800000, v0
	v_cndmask_b32_e32 v0, v0, v35, vcc
	v_mul_f32_e32 v0, v151, v0
	v_pk_mul_f32 v[36:37], v[22:23], v[0:1] op_sel_hi:[1,0]
	v_pk_mul_f32 v[38:39], v[30:31], v[0:1] op_sel_hi:[1,0]
	v_pk_mul_f32 v[36:37], v[94:95], v[36:37]
	v_pk_mul_f32 v[38:39], v[90:91], v[38:39]
	v_pk_mul_f32 v[42:43], v[32:33], v[0:1] op_sel_hi:[1,0]
	v_pk_fma_f32 v[40:41], v[38:39], 0, v[36:37] op_sel_hi:[1,0,1]
	v_pk_fma_f32 v[36:37], v[36:37], 0, v[38:39] op_sel_hi:[1,0,1] neg_lo:[1,0,0] neg_hi:[1,0,0]
	v_pk_mul_f32 v[38:39], v[24:25], v[0:1] op_sel_hi:[1,0]
	v_pk_mul_f32 v[42:43], v[92:93], v[42:43]
	v_pk_mul_f32 v[38:39], v[96:97], v[38:39]
	v_pk_mul_f32 v[46:47], v[26:27], v[0:1] op_sel_hi:[1,0]
	v_pk_fma_f32 v[44:45], v[42:43], 0, v[38:39] op_sel_hi:[1,0,1]
	v_pk_fma_f32 v[38:39], v[38:39], 0, v[42:43] op_sel_hi:[1,0,1] neg_lo:[1,0,0] neg_hi:[1,0,0]
	v_pk_mul_f32 v[42:43], v[18:19], v[0:1] op_sel_hi:[1,0]
	v_pk_mul_f32 v[46:47], v[82:83], v[46:47]
	v_pk_mul_f32 v[42:43], v[86:87], v[42:43]
	v_pk_mul_f32 v[50:51], v[28:29], v[0:1] op_sel_hi:[1,0]
	v_pk_fma_f32 v[48:49], v[46:47], 0, v[42:43] op_sel_hi:[1,0,1]
	v_pk_fma_f32 v[42:43], v[42:43], 0, v[46:47] op_sel_hi:[1,0,1] neg_lo:[1,0,0] neg_hi:[1,0,0]
	v_pk_mul_f32 v[46:47], v[20:21], v[0:1] op_sel_hi:[1,0]
	v_pk_mul_f32 v[50:51], v[84:85], v[50:51]
	v_pk_mul_f32 v[46:47], v[88:89], v[46:47]
	v_lshlrev_b32_e32 v0, 7, v34
	v_pk_fma_f32 v[52:53], v[50:51], 0, v[46:47] op_sel_hi:[1,0,1]
	v_pk_fma_f32 v[46:47], v[46:47], 0, v[50:51] op_sel_hi:[1,0,1] neg_lo:[1,0,0] neg_hi:[1,0,0]
	v_lshl_add_u64 v[50:51], s[0:1], 0, v[0:1]
	v_lshl_add_u64 v[50:51], v[50:51], 0, v[146:147]
	v_cvt_pk_bf16_f32 v36, v36, v37
	v_cvt_pk_bf16_f32 v37, v38, v39
	v_cvt_pk_bf16_f32 v38, v42, v43
	v_cvt_pk_bf16_f32 v39, v46, v47
	global_store_dwordx4 v[50:51], v[36:39], off
	s_nop 1
	v_cvt_pk_bf16_f32 v36, v40, v41
	v_cvt_pk_bf16_f32 v37, v44, v45
	v_cvt_pk_bf16_f32 v38, v48, v49
	v_cvt_pk_bf16_f32 v39, v52, v53
	global_store_dwordx4 v[50:51], v[36:39], off offset:64

; DI u16 f2bf(float a) { return (u16)(pack_bf16(a, 0.f) & 0xffffu); }
;   DI void operator()(const f32x4 (&acc)[2][2][4][2], const Unit& u, int wr, int wc, int fr, int fq) const {
;     ...
;         const int t = u.pm * BM + ai * HALF + wr * 64 + m * 16 + fr;
;         int b, pos;
;         if (rowbase == 0) { b = t >> 12; pos = t & 4095; } else { b = t >> 8; pos = 4096 + (t & 255); }
;         u16* base = qkv + (size_t)(b * 32 + chunk) * LTOT * 64;
;         if (isV) {
; #pragma unroll
;           for (int bj = 0; bj < 2; ++bj)
; #pragma unroll
;             for (int n = 0; n < 2; ++n)
; #pragma unroll
;               for (int e = 0; e < 4; ++e) {
;                 int d = 32 * bj + 8 * fq + 4 * n + e;
;                 base[(size_t)d * LTOT + pos] = f2bf(acc[ai][bj][m][n][e]);
;               }
;         } else {
;           float ss = 0.f;
; #pragma unroll
;           for (int bj = 0; bj < 2; ++bj)
; #pragma unroll
;             for (int n = 0; n < 2; ++n)
; #pragma unroll
;               for (int e = 0; e < 4; ++e) ss += acc[ai][bj][m][n][e] * acc[ai][bj][m][n][e];
;           ss += __shfl_xor(ss, 16);
;           ss += __shfl_xor(ss, 32);
;           const float rinv = rsqrtf(ss * (1.f / 64.f) + EPSV);
;           float o1[8], o2[8];
; #pragma unroll
;           for (int n = 0; n < 2; ++n) {
;             f32x4 cs0 = (f32x4){1.f, 0.f, 1.f, 0.f}, cs1 = cs0;
;             if (ropeT) { cs0 = csr[m & 1][n][0]; cs1 = csr[m & 1][n][1]; }
; #pragma unroll
;             for (int e = 0; e < 4; ++e) {
;               float x1 = acc[ai][0][m][n][e] * (rinv * qs) * g4[0][n][e];
;               float x2 = acc[ai][1][m][n][e] * (rinv * qs) * g4[1][n][e];
;               float c = (e < 2) ? cs0[2 * e] : cs1[2 * (e - 2)], s = (e < 2) ? cs0[2 * e + 1] : cs1[2 * (e - 2) + 1];
;               o1[n * 4 + e] = x1 * c - x2 * s;
;               o2[n * 4 + e] = x2 * c + x1 * s;
;             }
;           }
;           u16* dst = base + (size_t)pos * 64 + 8 * fq;
;           *(uint4*)(dst) = make_uint4(pack_bf16(o1[0], o1[1]), pack_bf16(o1[2], o1[3]), pack_bf16(o1[4], o1[5]), pack_bf16(o1[6], o1[7]));
;           *(uint4*)(dst + 32) = make_uint4(pack_bf16(o2[0], o2[1]), pack_bf16(o2[2], o2[3]), pack_bf16(o2[4], o2[5]), pack_bf16(o2[6], o2[7]));
.LBB0_869:
	s_add_i32 s0, s15, 0xb0
	s_add_i32 s1, s0, s10
	s_and_b32 s0, s0, 0xf0
	v_or_b32_e32 v0, s0, v150
	s_ashr_i32 s0, s1, 3
	s_andn2_b32 s0, s0, 31
	s_add_i32 s0, s0, s8
	s_mul_hi_i32 s1, s0, 0x88000
	s_mul_i32 s0, s0, 0x88000
	s_add_u32 s0, s88, s0
	v_or_b32_e32 v18, 0x1000, v0
	s_addc_u32 s1, s89, s1
	s_and_b64 vcc, exec, s[4:5]
	s_mov_b64 s[2:3], -1
	s_cbranch_vccnz .LBB0_871
	v_mul_f32_e32 v0, v15, v15
	v_fmac_f32_e32 v0, v14, v14
	v_fmac_f32_e32 v0, v16, v16
	v_fmac_f32_e32 v0, v17, v17
	v_fmac_f32_e32 v0, v10, v10
	v_fmac_f32_e32 v0, v11, v11
	v_fmac_f32_e32 v0, v12, v12
	v_fmac_f32_e32 v0, v13, v13
	v_pk_mul_f32 v[22:23], v[6:7], v[6:7]
	v_pk_mul_f32 v[20:21], v[8:9], v[8:9]
	v_add_f32_e32 v0, v22, v0
	v_add_f32_e32 v0, v23, v0
	v_add_f32_e32 v0, v20, v0
	v_add_f32_e32 v0, v21, v0
	v_pk_mul_f32 v[22:23], v[2:3], v[2:3]
	v_pk_mul_f32 v[20:21], v[4:5], v[4:5]
	v_add_f32_e32 v0, v22, v0
	v_add_f32_e32 v0, v23, v0
	v_add_f32_e32 v0, v20, v0
	v_add_f32_e32 v0, v21, v0
	v_mov_b32_e32 v147, v1
	v_mov_b32_e32 v19, v0
	s_nop 1
	v_permlane16_swap_b32_e32 v0, v19
	s_mov_b64 s[2:3], 0
	s_waitcnt lgkmcnt(0)
	v_add_f32_e32 v0, v0, v19
	s_nop 1
	v_mov_b32_e32 v19, v0
	s_nop 1
	v_permlane32_swap_b32_e32 v0, v19
	s_waitcnt lgkmcnt(0)
	v_add_f32_e32 v0, v0, v19
	v_fmamk_f32 v0, v0, 0x3c800000, v210
	v_mul_f32_e32 v19, 0x4b800000, v0
	v_cmp_gt_f32_e32 vcc, s11, v0
	s_nop 1
	v_cndmask_b32_e32 v0, v0, v19, vcc
	v_rsq_f32_e32 v0, v0
	s_nop 0
	v_mul_f32_e32 v19, 0x45800000, v0
	v_cndmask_b32_e32 v0, v0, v19, vcc
	v_mul_f32_e32 v0, v151, v0
	v_pk_mul_f32 v[20:21], v[6:7], v[0:1] op_sel_hi:[1,0]
	v_pk_mul_f32 v[22:23], v[14:15], v[0:1] op_sel_hi:[1,0]
	v_pk_mul_f32 v[20:21], v[94:95], v[20:21]
	v_pk_mul_f32 v[22:23], v[90:91], v[22:23]
	v_pk_mul_f32 v[26:27], v[16:17], v[0:1] op_sel_hi:[1,0]
	v_pk_fma_f32 v[24:25], v[22:23], 0, v[20:21] op_sel_hi:[1,0,1]
	v_pk_fma_f32 v[20:21], v[20:21], 0, v[22:23] op_sel_hi:[1,0,1] neg_lo:[1,0,0] neg_hi:[1,0,0]
	v_pk_mul_f32 v[22:23], v[8:9], v[0:1] op_sel_hi:[1,0]
	v_pk_mul_f32 v[26:27], v[92:93], v[26:27]
	v_pk_mul_f32 v[22:23], v[96:97], v[22:23]
	v_pk_mul_f32 v[30:31], v[10:11], v[0:1] op_sel_hi:[1,0]
	v_pk_fma_f32 v[28:29], v[26:27], 0, v[22:23] op_sel_hi:[1,0,1]
	v_pk_fma_f32 v[22:23], v[22:23], 0, v[26:27] op_sel_hi:[1,0,1] neg_lo:[1,0,0] neg_hi:[1,0,0]
	v_pk_mul_f32 v[26:27], v[2:3], v[0:1] op_sel_hi:[1,0]
	v_pk_mul_f32 v[30:31], v[82:83], v[30:31]
	v_pk_mul_f32 v[26:27], v[86:87], v[26:27]
	v_pk_mul_f32 v[34:35], v[12:13], v[0:1] op_sel_hi:[1,0]
	v_pk_fma_f32 v[32:33], v[30:31], 0, v[26:27] op_sel_hi:[1,0,1]
	v_pk_fma_f32 v[26:27], v[26:27], 0, v[30:31] op_sel_hi:[1,0,1] neg_lo:[1,0,0] neg_hi:[1,0,0]
	v_pk_mul_f32 v[30:31], v[4:5], v[0:1] op_sel_hi:[1,0]
	v_pk_mul_f32 v[34:35], v[84:85], v[34:35]
	v_pk_mul_f32 v[30:31], v[88:89], v[30:31]
	v_lshlrev_b32_e32 v0, 7, v18
	v_pk_fma_f32 v[36:37], v[34:35], 0, v[30:31] op_sel_hi:[1,0,1]
	v_pk_fma_f32 v[30:31], v[30:31], 0, v[34:35] op_sel_hi:[1,0,1] neg_lo:[1,0,0] neg_hi:[1,0,0]
	v_lshl_add_u64 v[34:35], s[0:1], 0, v[0:1]
	v_lshl_add_u64 v[34:35], v[34:35], 0, v[146:147]
	v_cvt_pk_bf16_f32 v20, v20, v21
	v_cvt_pk_bf16_f32 v21, v22, v23
	v_cvt_pk_bf16_f32 v22, v26, v27
	v_cvt_pk_bf16_f32 v23, v30, v31
	global_store_dwordx4 v[34:35], v[20:23], off
	s_nop 1
	v_cvt_pk_bf16_f32 v20, v24, v25
	v_cvt_pk_bf16_f32 v21, v28, v29
	v_cvt_pk_bf16_f32 v22, v32, v33
	v_cvt_pk_bf16_f32 v23, v36, v37
	global_store_dwordx4 v[34:35], v[20:23], off offset:64
